# branch projection epilogues: rolling prefetch of merge-gate and running-merge tiles
# baseline (speedup 1.0000x reference)
; __device__ __forceinline__ unsigned cvt_pk_bf16(float lo, float hi) { const f32x2_t v = {lo, hi}; const bf16x2_t b = __builtin_convertvector(v, bf16x2_t); return __builtin_bit_cast(unsigned, b); }
;     __device__ __forceinline__ void operator()(const Acc& acc, const Unit& u, int wr, int wc, int fr, int fq) const {
;     ...
; #pragma unroll
;         for (int ai = 0; ai < 2; ++ai)
; #pragma unroll
;             for (int m = 0; m < 4; ++m) {
;                 asm volatile("" ::: "memory");
;                 const int r = row0 + ai * HALF + m * 16;
; #pragma unroll
;                 for (int bj = 0; bj < 2; ++bj) {
;                     const int c = col0 + bj * HALF; const size_t off = (size_t)r * D + c;
;                     const u32x4 gw = *(const u32x4*)(gates + (size_t)r * 6144 + br * D + c);
;                     f32x4 v0, v1;
;                     v0[0] = acc[ai][bj][m][0][0] * bflo(gw.x); v0[1] = acc[ai][bj][m][0][1] * bfhi(gw.x); v0[2] = acc[ai][bj][m][0][2] * bflo(gw.y); v0[3] = acc[ai][bj][m][0][3] * bfhi(gw.y);
;                     v1[0] = acc[ai][bj][m][1][0] * bflo(gw.z); v1[1] = acc[ai][bj][m][1][1] * bfhi(gw.z); v1[2] = acc[ai][bj][m][1][2] * bflo(gw.w); v1[3] = acc[ai][bj][m][1][3] * bfhi(gw.w);
;                     if (br > 0) { const u32x4 ma = *(const u32x4*)(prev + off);
;                         v0[0] += bflo(ma.x); v0[1] += bfhi(ma.x); v0[2] += bflo(ma.y); v0[3] += bfhi(ma.y); v1[0] += bflo(ma.z); v1[1] += bfhi(ma.z); v1[2] += bflo(ma.w); v1[3] += bfhi(ma.w); }
;                     u32x4 w; w.x = cvt_pk_bf16(v0[0], v0[1]); w.y = cvt_pk_bf16(v0[2], v0[3]); w.z = cvt_pk_bf16(v1[0], v1[1]); w.w = cvt_pk_bf16(v1[2], v1[3]);
;                     *(u32x4*)(dst + off) = w;
;                 }
.LBB0_190:
	v_lshl_add_u32 v140, s62, 8, v146
	v_lshl_or_b32 v138, s42, 8, v148
	v_ashrrev_i32_e32 v141, 31, v140
	v_lshlrev_b64 v[158:159], 11, v[140:141]
	v_ashrrev_i32_e32 v139, 31, v138
	v_mov_b64_e32 v[144:145], s[6:7]
	v_lshl_add_u64 v[154:155], v[158:159], 0, v[138:139]
	v_mad_i64_i32 v[142:143], s[2:3], v140, s26, v[144:145]
	v_lshl_add_u64 v[166:167], v[142:143], 0, s[56:57]
	v_lshlrev_b64 v[142:143], 1, v[138:139]
	v_lshlrev_b64 v[170:171], 1, v[154:155]
	v_lshl_add_u64 v[150:151], v[166:167], 0, v[142:143]
	v_lshl_add_u64 v[154:155], s[16:17], 0, v[170:171]
	v_subrev_u32_e32 v212, s6, v150
	v_subrev_u32_e32 v213, s16, v154
	global_load_dwordx4 v[176:179], v212, s[6:7]
	global_load_dwordx4 v[180:183], v213, s[16:17]
	global_load_dwordx4 v[184:187], v212, s[6:7] offset:256
	global_load_dwordx4 v[188:191], v213, s[16:17] offset:256
	v_add_u32_e32 v214, 0x30000, v212
	global_load_dwordx4 v[192:195], v214, s[6:7]
	v_add_u32_e32 v214, 0x10000, v213
	global_load_dwordx4 v[196:199], v214, s[16:17]
	v_add_u32_e32 v214, 0x30000, v212
	global_load_dwordx4 v[200:203], v214, s[6:7] offset:256
	v_add_u32_e32 v214, 0x10000, v213
	global_load_dwordx4 v[204:207], v214, s[16:17] offset:256
	v_add_u32_e32 v214, 0x60000, v212
	global_load_dwordx4 v[208:211], v214, s[6:7]
	s_waitcnt vmcnt(8)
	s_nop 1
	v_mov_b64_e32 v[150:151], v[176:177]
	v_mov_b64_e32 v[152:153], v[178:179]
	v_add_u32_e32 v214, 0x20000, v213
	global_load_dwordx4 v[176:179], v214, s[16:17]
	s_mov_b64 s[24:25], -1
	s_waitcnt vmcnt(8)
	s_nop 1
	v_mov_b64_e32 v[154:155], v[180:181]
	v_mov_b64_e32 v[156:157], v[182:183]
	v_add_u32_e32 v214, 0x60000, v212
	global_load_dwordx4 v[180:183], v214, s[6:7] offset:256
	s_andn2_b64 vcc, exec, s[4:5]
	v_lshlrev_b32_e32 v172, 16, v150
	v_and_b32_e32 v173, 0xffff0000, v150
	v_lshlrev_b32_e32 v174, 16, v154
	v_and_b32_e32 v175, 0xffff0000, v154
	v_lshlrev_b32_e32 v150, 16, v151
	v_and_b32_e32 v151, 0xffff0000, v151
	v_lshlrev_b32_e32 v154, 16, v155
	v_and_b32_e32 v155, 0xffff0000, v155
	v_pk_fma_f32 v[126:127], v[126:127], v[150:151], v[154:155]
	v_lshlrev_b32_e32 v150, 16, v152
	v_and_b32_e32 v151, 0xffff0000, v152
	v_lshlrev_b32_e32 v154, 16, v156
	v_and_b32_e32 v155, 0xffff0000, v156
	v_pk_fma_f32 v[150:151], v[120:121], v[150:151], v[154:155]
	v_lshlrev_b32_e32 v120, 16, v153
	v_and_b32_e32 v121, 0xffff0000, v153
	v_lshlrev_b32_e32 v152, 16, v157
	v_and_b32_e32 v153, 0xffff0000, v157
	v_pk_fma_f32 v[124:125], v[124:125], v[172:173], v[174:175]
	v_pk_fma_f32 v[152:153], v[122:123], v[120:121], v[152:153]
	v_cvt_pk_bf16_f32 v120, v124, v125
	v_cvt_pk_bf16_f32 v121, v126, v127
	v_cvt_pk_bf16_f32 v122, v150, v151
	v_cvt_pk_bf16_f32 v123, v152, v153
	v_lshl_add_u64 v[124:125], s[88:89], 0, v[170:171]
	global_store_dwordx4 v[124:125], v[120:123], off
	s_nop 1
	v_or_b32_e32 v120, 0x80, v138
	v_ashrrev_i32_e32 v121, 31, v120
	v_lshl_add_u64 v[150:151], v[158:159], 0, v[120:121]
	v_lshlrev_b64 v[122:123], 1, v[120:121]
	v_lshlrev_b64 v[154:155], 1, v[150:151]
	v_lshl_add_u64 v[124:125], v[166:167], 0, v[122:123]
	v_lshl_add_u64 v[150:151], s[16:17], 0, v[154:155]
	s_waitcnt vmcnt(9)
	s_nop 1
	v_mov_b64_e32 v[124:125], v[184:185]
	v_mov_b64_e32 v[126:127], v[186:187]
	v_add_u32_e32 v214, 0x20000, v213
	global_load_dwordx4 v[184:187], v214, s[16:17] offset:256
	s_nop 0
	s_waitcnt vmcnt(9)
	s_nop 1
	v_mov_b64_e32 v[150:151], v[188:189]
	v_mov_b64_e32 v[152:153], v[190:191]
	v_add_u32_e32 v214, 0x90000, v212
	global_load_dwordx4 v[188:191], v214, s[6:7]
	v_lshlrev_b32_e32 v156, 16, v124
	v_and_b32_e32 v157, 0xffff0000, v124
	v_lshlrev_b32_e32 v158, 16, v150
	v_and_b32_e32 v159, 0xffff0000, v150
	v_lshlrev_b32_e32 v124, 16, v125
	v_and_b32_e32 v125, 0xffff0000, v125
	v_lshlrev_b32_e32 v150, 16, v151
	v_and_b32_e32 v151, 0xffff0000, v151
	v_pk_fma_f32 v[118:119], v[118:119], v[124:125], v[150:151]
	v_lshlrev_b32_e32 v124, 16, v126
	v_and_b32_e32 v125, 0xffff0000, v126
	v_lshlrev_b32_e32 v150, 16, v152
	v_and_b32_e32 v151, 0xffff0000, v152
	v_pk_fma_f32 v[124:125], v[112:113], v[124:125], v[150:151]
	v_lshlrev_b32_e32 v112, 16, v127
	v_and_b32_e32 v113, 0xffff0000, v127
	v_lshlrev_b32_e32 v126, 16, v153
	v_and_b32_e32 v127, 0xffff0000, v153
	v_pk_fma_f32 v[116:117], v[116:117], v[156:157], v[158:159]
	v_pk_fma_f32 v[126:127], v[114:115], v[112:113], v[126:127]
	v_cvt_pk_bf16_f32 v112, v116, v117
	v_cvt_pk_bf16_f32 v113, v118, v119
	v_cvt_pk_bf16_f32 v114, v124, v125
	v_cvt_pk_bf16_f32 v115, v126, v127
	v_lshl_add_u64 v[116:117], s[88:89], 0, v[154:155]
	global_store_dwordx4 v[116:117], v[112:115], off
	s_nop 1
	v_or_b32_e32 v114, 16, v140
	v_ashrrev_i32_e32 v115, 31, v114
	v_lshlrev_b64 v[112:113], 11, v[114:115]
	v_lshl_add_u64 v[124:125], v[112:113], 0, v[138:139]
	v_mad_i64_i32 v[114:115], s[2:3], v114, s26, v[144:145]
	v_lshl_add_u64 v[114:115], v[114:115], 0, s[56:57]
	v_lshlrev_b64 v[150:151], 1, v[124:125]
	v_lshl_add_u64 v[116:117], v[114:115], 0, v[142:143]
	v_lshl_add_u64 v[124:125], s[16:17], 0, v[150:151]
	s_waitcnt vmcnt(10)
	s_nop 1
	v_mov_b64_e32 v[116:117], v[192:193]
	v_mov_b64_e32 v[118:119], v[194:195]
	v_add_u32_e32 v214, 0x30000, v213
	global_load_dwordx4 v[192:195], v214, s[16:17]
	s_nop 0
	s_waitcnt vmcnt(10)
; __device__ __forceinline__ unsigned cvt_pk_bf16(float lo, float hi) { const f32x2_t v = {lo, hi}; const bf16x2_t b = __builtin_convertvector(v, bf16x2_t); return __builtin_bit_cast(unsigned, b); }
;     __device__ __forceinline__ void operator()(const Acc& acc, const Unit& u, int wr, int wc, int fr, int fq) const {
;     ...
; #pragma unroll
;         for (int ai = 0; ai < 2; ++ai)
; #pragma unroll
;             for (int m = 0; m < 4; ++m) {
;                 asm volatile("" ::: "memory");
;                 const int r = row0 + ai * HALF + m * 16;
; #pragma unroll
;                 for (int bj = 0; bj < 2; ++bj) {
;                     const int c = col0 + bj * HALF; const size_t off = (size_t)r * D + c;
;                     const u32x4 gw = *(const u32x4*)(gates + (size_t)r * 6144 + br * D + c);
;                     f32x4 v0, v1;
;                     v0[0] = acc[ai][bj][m][0][0] * bflo(gw.x); v0[1] = acc[ai][bj][m][0][1] * bfhi(gw.x); v0[2] = acc[ai][bj][m][0][2] * bflo(gw.y); v0[3] = acc[ai][bj][m][0][3] * bfhi(gw.y);
;                     v1[0] = acc[ai][bj][m][1][0] * bflo(gw.z); v1[1] = acc[ai][bj][m][1][1] * bfhi(gw.z); v1[2] = acc[ai][bj][m][1][2] * bflo(gw.w); v1[3] = acc[ai][bj][m][1][3] * bfhi(gw.w);
;                     if (br > 0) { const u32x4 ma = *(const u32x4*)(prev + off);
;                         v0[0] += bflo(ma.x); v0[1] += bfhi(ma.x); v0[2] += bflo(ma.y); v0[3] += bfhi(ma.y); v1[0] += bflo(ma.z); v1[1] += bfhi(ma.z); v1[2] += bflo(ma.w); v1[3] += bfhi(ma.w); }
;                     u32x4 w; w.x = cvt_pk_bf16(v0[0], v0[1]); w.y = cvt_pk_bf16(v0[2], v0[3]); w.z = cvt_pk_bf16(v1[0], v1[1]); w.w = cvt_pk_bf16(v1[2], v1[3]);
;                     *(u32x4*)(dst + off) = w;
;                 }
	s_nop 1
	v_mov_b64_e32 v[124:125], v[196:197]
	v_mov_b64_e32 v[126:127], v[198:199]
	v_add_u32_e32 v214, 0x90000, v212
	global_load_dwordx4 v[196:199], v214, s[6:7] offset:256
	v_lshlrev_b32_e32 v152, 16, v116
	v_and_b32_e32 v153, 0xffff0000, v116
	v_lshlrev_b32_e32 v154, 16, v124
	v_and_b32_e32 v155, 0xffff0000, v124
	v_lshlrev_b32_e32 v116, 16, v117
	v_and_b32_e32 v117, 0xffff0000, v117
	v_lshlrev_b32_e32 v124, 16, v125
	v_and_b32_e32 v125, 0xffff0000, v125
	v_pk_fma_f32 v[110:111], v[110:111], v[116:117], v[124:125]
	v_lshlrev_b32_e32 v116, 16, v118
	v_and_b32_e32 v117, 0xffff0000, v118
	v_lshlrev_b32_e32 v124, 16, v126
	v_and_b32_e32 v125, 0xffff0000, v126
	v_pk_fma_f32 v[116:117], v[104:105], v[116:117], v[124:125]
	v_lshlrev_b32_e32 v104, 16, v119
	v_and_b32_e32 v105, 0xffff0000, v119
	v_lshlrev_b32_e32 v118, 16, v127
	v_and_b32_e32 v119, 0xffff0000, v127
	v_pk_fma_f32 v[108:109], v[108:109], v[152:153], v[154:155]
	v_pk_fma_f32 v[118:119], v[106:107], v[104:105], v[118:119]
	v_cvt_pk_bf16_f32 v104, v108, v109
	v_cvt_pk_bf16_f32 v105, v110, v111
	v_cvt_pk_bf16_f32 v106, v116, v117
	v_cvt_pk_bf16_f32 v107, v118, v119
	v_lshl_add_u64 v[108:109], s[88:89], 0, v[150:151]
	global_store_dwordx4 v[108:109], v[104:107], off
	v_lshl_add_u64 v[108:109], v[112:113], 0, v[120:121]
	v_lshlrev_b64 v[112:113], 1, v[108:109]
	v_lshl_add_u64 v[104:105], v[114:115], 0, v[122:123]
	v_lshl_add_u64 v[108:109], s[16:17], 0, v[112:113]
	s_waitcnt vmcnt(11)
	s_nop 1
	v_mov_b64_e32 v[104:105], v[200:201]
	v_mov_b64_e32 v[106:107], v[202:203]
	v_add_u32_e32 v214, 0x30000, v213
	global_load_dwordx4 v[200:203], v214, s[16:17] offset:256
	s_nop 0
	s_waitcnt vmcnt(11)
	s_nop 1
	v_mov_b64_e32 v[108:109], v[204:205]
	v_mov_b64_e32 v[110:111], v[206:207]
	v_add_u32_e32 v214, 0x180000, v212
	global_load_dwordx4 v[204:207], v214, s[6:7]
	v_lshlrev_b32_e32 v114, 16, v104
	v_and_b32_e32 v115, 0xffff0000, v104
	v_lshlrev_b32_e32 v116, 16, v108
	v_and_b32_e32 v117, 0xffff0000, v108
	v_lshlrev_b32_e32 v104, 16, v105
	v_and_b32_e32 v105, 0xffff0000, v105
	v_lshlrev_b32_e32 v108, 16, v109
	v_and_b32_e32 v109, 0xffff0000, v109
	v_pk_fma_f32 v[102:103], v[102:103], v[104:105], v[108:109]
	v_lshlrev_b32_e32 v104, 16, v106
	v_and_b32_e32 v105, 0xffff0000, v106
	v_lshlrev_b32_e32 v108, 16, v110
	v_and_b32_e32 v109, 0xffff0000, v110
	v_pk_fma_f32 v[104:105], v[96:97], v[104:105], v[108:109]
	v_lshlrev_b32_e32 v96, 16, v107
	v_and_b32_e32 v97, 0xffff0000, v107
	v_lshlrev_b32_e32 v106, 16, v111
	v_and_b32_e32 v107, 0xffff0000, v111
	v_pk_fma_f32 v[100:101], v[100:101], v[114:115], v[116:117]
	v_pk_fma_f32 v[106:107], v[98:99], v[96:97], v[106:107]
	v_cvt_pk_bf16_f32 v96, v100, v101
	v_cvt_pk_bf16_f32 v97, v102, v103
	v_cvt_pk_bf16_f32 v98, v104, v105
	v_cvt_pk_bf16_f32 v99, v106, v107
	v_lshl_add_u64 v[100:101], s[88:89], 0, v[112:113]
	global_store_dwordx4 v[100:101], v[96:99], off
	s_nop 1
	v_or_b32_e32 v98, 32, v140
	v_ashrrev_i32_e32 v99, 31, v98
	v_lshlrev_b64 v[96:97], 11, v[98:99]
	v_lshl_add_u64 v[104:105], v[96:97], 0, v[138:139]
	v_mad_i64_i32 v[98:99], s[2:3], v98, s26, v[144:145]
	v_lshl_add_u64 v[98:99], v[98:99], 0, s[56:57]
	v_lshlrev_b64 v[108:109], 1, v[104:105]
	v_lshl_add_u64 v[100:101], v[98:99], 0, v[142:143]
	v_lshl_add_u64 v[104:105], s[16:17], 0, v[108:109]
	s_waitcnt vmcnt(12)
	s_nop 1
	v_mov_b64_e32 v[100:101], v[208:209]
	v_mov_b64_e32 v[102:103], v[210:211]
	v_add_u32_e32 v214, 0x80000, v213
	global_load_dwordx4 v[208:211], v214, s[16:17]
	s_nop 0
	s_waitcnt vmcnt(12)
	s_nop 1
	v_mov_b64_e32 v[104:105], v[176:177]
	v_mov_b64_e32 v[106:107], v[178:179]
	v_add_u32_e32 v214, 0x180000, v212
	global_load_dwordx4 v[176:179], v214, s[6:7] offset:256
	v_lshlrev_b32_e32 v110, 16, v100
	v_and_b32_e32 v111, 0xffff0000, v100
	v_lshlrev_b32_e32 v112, 16, v104
	v_and_b32_e32 v113, 0xffff0000, v104
	v_lshlrev_b32_e32 v100, 16, v101
	v_and_b32_e32 v101, 0xffff0000, v101
	v_lshlrev_b32_e32 v104, 16, v105
	v_and_b32_e32 v105, 0xffff0000, v105
	v_pk_fma_f32 v[94:95], v[94:95], v[100:101], v[104:105]
	v_lshlrev_b32_e32 v100, 16, v102
	v_and_b32_e32 v101, 0xffff0000, v102
	v_lshlrev_b32_e32 v104, 16, v106
	v_and_b32_e32 v105, 0xffff0000, v106
	v_pk_fma_f32 v[100:101], v[88:89], v[100:101], v[104:105]
	v_lshlrev_b32_e32 v88, 16, v103
	v_and_b32_e32 v89, 0xffff0000, v103
	v_lshlrev_b32_e32 v102, 16, v107
	v_and_b32_e32 v103, 0xffff0000, v107
	v_pk_fma_f32 v[92:93], v[92:93], v[110:111], v[112:113]
	v_pk_fma_f32 v[102:103], v[90:91], v[88:89], v[102:103]
	v_cvt_pk_bf16_f32 v88, v92, v93
	v_cvt_pk_bf16_f32 v89, v94, v95
	v_cvt_pk_bf16_f32 v90, v100, v101
	v_cvt_pk_bf16_f32 v91, v102, v103
	v_lshl_add_u64 v[92:93], s[88:89], 0, v[108:109]
	global_store_dwordx4 v[92:93], v[88:91], off
	v_lshl_add_u64 v[92:93], v[96:97], 0, v[120:121]
	v_lshlrev_b64 v[96:97], 1, v[92:93]
	v_lshl_add_u64 v[88:89], v[98:99], 0, v[122:123]
	v_lshl_add_u64 v[92:93], s[16:17], 0, v[96:97]
	s_waitcnt vmcnt(13)
	s_nop 1
	v_mov_b64_e32 v[88:89], v[180:181]
	v_mov_b64_e32 v[90:91], v[182:183]
	v_add_u32_e32 v214, 0x80000, v213
	global_load_dwordx4 v[180:183], v214, s[16:17] offset:256
	s_nop 0
	s_waitcnt vmcnt(12)
; __device__ __forceinline__ unsigned cvt_pk_bf16(float lo, float hi) { const f32x2_t v = {lo, hi}; const bf16x2_t b = __builtin_convertvector(v, bf16x2_t); return __builtin_bit_cast(unsigned, b); }
;     __device__ __forceinline__ void operator()(const Acc& acc, const Unit& u, int wr, int wc, int fr, int fq) const {
;     ...
; #pragma unroll
;         for (int ai = 0; ai < 2; ++ai)
; #pragma unroll
;             for (int m = 0; m < 4; ++m) {
;                 asm volatile("" ::: "memory");
;                 const int r = row0 + ai * HALF + m * 16;
; #pragma unroll
;                 for (int bj = 0; bj < 2; ++bj) {
;                     const int c = col0 + bj * HALF; const size_t off = (size_t)r * D + c;
;                     const u32x4 gw = *(const u32x4*)(gates + (size_t)r * 6144 + br * D + c);
;                     f32x4 v0, v1;
;                     v0[0] = acc[ai][bj][m][0][0] * bflo(gw.x); v0[1] = acc[ai][bj][m][0][1] * bfhi(gw.x); v0[2] = acc[ai][bj][m][0][2] * bflo(gw.y); v0[3] = acc[ai][bj][m][0][3] * bfhi(gw.y);
;                     v1[0] = acc[ai][bj][m][1][0] * bflo(gw.z); v1[1] = acc[ai][bj][m][1][1] * bfhi(gw.z); v1[2] = acc[ai][bj][m][1][2] * bflo(gw.w); v1[3] = acc[ai][bj][m][1][3] * bfhi(gw.w);
;                     if (br > 0) { const u32x4 ma = *(const u32x4*)(prev + off);
;                         v0[0] += bflo(ma.x); v0[1] += bfhi(ma.x); v0[2] += bflo(ma.y); v0[3] += bfhi(ma.y); v1[0] += bflo(ma.z); v1[1] += bfhi(ma.z); v1[2] += bflo(ma.w); v1[3] += bfhi(ma.w); }
;                     u32x4 w; w.x = cvt_pk_bf16(v0[0], v0[1]); w.y = cvt_pk_bf16(v0[2], v0[3]); w.z = cvt_pk_bf16(v1[0], v1[1]); w.w = cvt_pk_bf16(v1[2], v1[3]);
;                     *(u32x4*)(dst + off) = w;
;                 }
	s_nop 1
	v_mov_b64_e32 v[92:93], v[184:185]
	v_mov_b64_e32 v[94:95], v[186:187]
	v_add_u32_e32 v214, 0x1b0000, v212
	global_load_dwordx4 v[184:187], v214, s[6:7]
	v_lshlrev_b32_e32 v98, 16, v88
	v_and_b32_e32 v99, 0xffff0000, v88
	v_lshlrev_b32_e32 v100, 16, v92
	v_and_b32_e32 v101, 0xffff0000, v92
	v_lshlrev_b32_e32 v88, 16, v89
	v_and_b32_e32 v89, 0xffff0000, v89
	v_lshlrev_b32_e32 v92, 16, v93
	v_and_b32_e32 v93, 0xffff0000, v93
	v_pk_fma_f32 v[86:87], v[86:87], v[88:89], v[92:93]
	v_lshlrev_b32_e32 v88, 16, v90
	v_and_b32_e32 v89, 0xffff0000, v90
	v_lshlrev_b32_e32 v92, 16, v94
	v_and_b32_e32 v93, 0xffff0000, v94
	v_pk_fma_f32 v[88:89], v[80:81], v[88:89], v[92:93]
	v_lshlrev_b32_e32 v80, 16, v91
	v_and_b32_e32 v81, 0xffff0000, v91
	v_lshlrev_b32_e32 v90, 16, v95
	v_and_b32_e32 v91, 0xffff0000, v95
	v_pk_fma_f32 v[84:85], v[84:85], v[98:99], v[100:101]
	v_pk_fma_f32 v[90:91], v[82:83], v[80:81], v[90:91]
	v_cvt_pk_bf16_f32 v80, v84, v85
	v_cvt_pk_bf16_f32 v81, v86, v87
	v_cvt_pk_bf16_f32 v82, v88, v89
	v_cvt_pk_bf16_f32 v83, v90, v91
	v_lshl_add_u64 v[84:85], s[88:89], 0, v[96:97]
	global_store_dwordx4 v[84:85], v[80:83], off
	s_nop 1
	v_or_b32_e32 v82, 48, v140
	v_ashrrev_i32_e32 v83, 31, v82
	v_lshlrev_b64 v[80:81], 11, v[82:83]
	v_lshl_add_u64 v[88:89], v[80:81], 0, v[138:139]
	v_mad_i64_i32 v[82:83], s[2:3], v82, s26, v[144:145]
	v_lshl_add_u64 v[82:83], v[82:83], 0, s[56:57]
	v_lshlrev_b64 v[92:93], 1, v[88:89]
	v_lshl_add_u64 v[84:85], v[82:83], 0, v[142:143]
	v_lshl_add_u64 v[88:89], s[16:17], 0, v[92:93]
	s_waitcnt vmcnt(13)
	s_nop 1
	v_mov_b64_e32 v[84:85], v[188:189]
	v_mov_b64_e32 v[86:87], v[190:191]
	v_add_u32_e32 v214, 0x90000, v213
	global_load_dwordx4 v[188:191], v214, s[16:17]
	s_nop 0
	s_waitcnt vmcnt(12)
	s_nop 1
	v_mov_b64_e32 v[88:89], v[192:193]
	v_mov_b64_e32 v[90:91], v[194:195]
	v_add_u32_e32 v214, 0x1b0000, v212
	global_load_dwordx4 v[192:195], v214, s[6:7] offset:256
	v_lshlrev_b32_e32 v94, 16, v84
	v_and_b32_e32 v95, 0xffff0000, v84
	v_lshlrev_b32_e32 v96, 16, v88
	v_and_b32_e32 v97, 0xffff0000, v88
	v_lshlrev_b32_e32 v84, 16, v85
	v_and_b32_e32 v85, 0xffff0000, v85
	v_lshlrev_b32_e32 v88, 16, v89
	v_and_b32_e32 v89, 0xffff0000, v89
	v_pk_fma_f32 v[78:79], v[78:79], v[84:85], v[88:89]
	v_lshlrev_b32_e32 v84, 16, v86
	v_and_b32_e32 v85, 0xffff0000, v86
	v_lshlrev_b32_e32 v88, 16, v90
	v_and_b32_e32 v89, 0xffff0000, v90
	v_pk_fma_f32 v[84:85], v[72:73], v[84:85], v[88:89]
	v_lshlrev_b32_e32 v72, 16, v87
	v_and_b32_e32 v73, 0xffff0000, v87
	v_lshlrev_b32_e32 v86, 16, v91
	v_and_b32_e32 v87, 0xffff0000, v91
	v_pk_fma_f32 v[76:77], v[76:77], v[94:95], v[96:97]
	v_pk_fma_f32 v[86:87], v[74:75], v[72:73], v[86:87]
	v_cvt_pk_bf16_f32 v72, v76, v77
	v_cvt_pk_bf16_f32 v73, v78, v79
	v_cvt_pk_bf16_f32 v74, v84, v85
	v_cvt_pk_bf16_f32 v75, v86, v87
	v_lshl_add_u64 v[76:77], s[88:89], 0, v[92:93]
	global_store_dwordx4 v[76:77], v[72:75], off
	v_lshl_add_u64 v[76:77], v[80:81], 0, v[120:121]
	v_lshlrev_b64 v[80:81], 1, v[76:77]
	v_lshl_add_u64 v[72:73], v[82:83], 0, v[122:123]
	v_lshl_add_u64 v[76:77], s[16:17], 0, v[80:81]
	s_waitcnt vmcnt(13)
	s_nop 1
	v_mov_b64_e32 v[72:73], v[196:197]
	v_mov_b64_e32 v[74:75], v[198:199]
	v_add_u32_e32 v214, 0x90000, v213
	global_load_dwordx4 v[196:199], v214, s[16:17] offset:256
	s_nop 0
	s_waitcnt vmcnt(12)
	s_nop 1
	v_mov_b64_e32 v[76:77], v[200:201]
	v_mov_b64_e32 v[78:79], v[202:203]
	v_add_u32_e32 v214, 0x1e0000, v212
	global_load_dwordx4 v[200:203], v214, s[6:7]
	v_lshlrev_b32_e32 v82, 16, v72
	v_and_b32_e32 v83, 0xffff0000, v72
	v_lshlrev_b32_e32 v84, 16, v76
	v_and_b32_e32 v85, 0xffff0000, v76
	v_lshlrev_b32_e32 v72, 16, v73
	v_and_b32_e32 v73, 0xffff0000, v73
	v_lshlrev_b32_e32 v76, 16, v77
	v_and_b32_e32 v77, 0xffff0000, v77
	v_pk_fma_f32 v[70:71], v[70:71], v[72:73], v[76:77]
	v_lshlrev_b32_e32 v72, 16, v74
	v_and_b32_e32 v73, 0xffff0000, v74
	v_lshlrev_b32_e32 v76, 16, v78
	v_and_b32_e32 v77, 0xffff0000, v78
	v_pk_fma_f32 v[72:73], v[64:65], v[72:73], v[76:77]
	v_lshlrev_b32_e32 v64, 16, v75
	v_and_b32_e32 v65, 0xffff0000, v75
	v_lshlrev_b32_e32 v74, 16, v79
	v_and_b32_e32 v75, 0xffff0000, v79
	v_pk_fma_f32 v[68:69], v[68:69], v[82:83], v[84:85]
	v_pk_fma_f32 v[74:75], v[66:67], v[64:65], v[74:75]
	v_cvt_pk_bf16_f32 v64, v68, v69
	v_cvt_pk_bf16_f32 v65, v70, v71
	v_cvt_pk_bf16_f32 v66, v72, v73
	v_cvt_pk_bf16_f32 v67, v74, v75
	v_lshl_add_u64 v[68:69], s[88:89], 0, v[80:81]
	global_store_dwordx4 v[68:69], v[64:67], off
	s_nop 1
	v_add_u32_e32 v66, 0x80, v140
	v_ashrrev_i32_e32 v67, 31, v66
	v_lshlrev_b64 v[64:65], 11, v[66:67]
	v_lshl_add_u64 v[72:73], v[64:65], 0, v[138:139]
	v_mad_i64_i32 v[66:67], s[2:3], v66, s26, v[144:145]
	v_lshl_add_u64 v[66:67], v[66:67], 0, s[56:57]
	v_lshlrev_b64 v[76:77], 1, v[72:73]
	v_lshl_add_u64 v[68:69], v[66:67], 0, v[142:143]
	v_lshl_add_u64 v[72:73], s[16:17], 0, v[76:77]
	s_waitcnt vmcnt(13)
	s_nop 1
	v_mov_b64_e32 v[68:69], v[204:205]
	v_mov_b64_e32 v[70:71], v[206:207]
	v_add_u32_e32 v214, 0xa0000, v213
	global_load_dwordx4 v[204:207], v214, s[16:17]
	s_nop 0
	s_waitcnt vmcnt(12)
; __device__ __forceinline__ unsigned cvt_pk_bf16(float lo, float hi) { const f32x2_t v = {lo, hi}; const bf16x2_t b = __builtin_convertvector(v, bf16x2_t); return __builtin_bit_cast(unsigned, b); }
;     __device__ __forceinline__ void operator()(const Acc& acc, const Unit& u, int wr, int wc, int fr, int fq) const {
;     ...
; #pragma unroll
;         for (int ai = 0; ai < 2; ++ai)
; #pragma unroll
;             for (int m = 0; m < 4; ++m) {
;                 asm volatile("" ::: "memory");
;                 const int r = row0 + ai * HALF + m * 16;
; #pragma unroll
;                 for (int bj = 0; bj < 2; ++bj) {
;                     const int c = col0 + bj * HALF; const size_t off = (size_t)r * D + c;
;                     const u32x4 gw = *(const u32x4*)(gates + (size_t)r * 6144 + br * D + c);
;                     f32x4 v0, v1;
;                     v0[0] = acc[ai][bj][m][0][0] * bflo(gw.x); v0[1] = acc[ai][bj][m][0][1] * bfhi(gw.x); v0[2] = acc[ai][bj][m][0][2] * bflo(gw.y); v0[3] = acc[ai][bj][m][0][3] * bfhi(gw.y);
;                     v1[0] = acc[ai][bj][m][1][0] * bflo(gw.z); v1[1] = acc[ai][bj][m][1][1] * bfhi(gw.z); v1[2] = acc[ai][bj][m][1][2] * bflo(gw.w); v1[3] = acc[ai][bj][m][1][3] * bfhi(gw.w);
;                     if (br > 0) { const u32x4 ma = *(const u32x4*)(prev + off);
;                         v0[0] += bflo(ma.x); v0[1] += bfhi(ma.x); v0[2] += bflo(ma.y); v0[3] += bfhi(ma.y); v1[0] += bflo(ma.z); v1[1] += bfhi(ma.z); v1[2] += bflo(ma.w); v1[3] += bfhi(ma.w); }
;                     u32x4 w; w.x = cvt_pk_bf16(v0[0], v0[1]); w.y = cvt_pk_bf16(v0[2], v0[3]); w.z = cvt_pk_bf16(v1[0], v1[1]); w.w = cvt_pk_bf16(v1[2], v1[3]);
;                     *(u32x4*)(dst + off) = w;
;                 }
	s_nop 1
	v_mov_b64_e32 v[72:73], v[208:209]
	v_mov_b64_e32 v[74:75], v[210:211]
	v_add_u32_e32 v214, 0x1e0000, v212
	global_load_dwordx4 v[208:211], v214, s[6:7] offset:256
	v_lshlrev_b32_e32 v78, 16, v68
	v_and_b32_e32 v79, 0xffff0000, v68
	v_lshlrev_b32_e32 v80, 16, v72
	v_and_b32_e32 v81, 0xffff0000, v72
	v_lshlrev_b32_e32 v68, 16, v69
	v_and_b32_e32 v69, 0xffff0000, v69
	v_lshlrev_b32_e32 v72, 16, v73
	v_and_b32_e32 v73, 0xffff0000, v73
	v_pk_fma_f32 v[62:63], v[62:63], v[68:69], v[72:73]
	v_lshlrev_b32_e32 v68, 16, v70
	v_and_b32_e32 v69, 0xffff0000, v70
	v_lshlrev_b32_e32 v72, 16, v74
	v_and_b32_e32 v73, 0xffff0000, v74
	v_pk_fma_f32 v[68:69], v[56:57], v[68:69], v[72:73]
	v_lshlrev_b32_e32 v56, 16, v71
	v_and_b32_e32 v57, 0xffff0000, v71
	v_lshlrev_b32_e32 v70, 16, v75
	v_and_b32_e32 v71, 0xffff0000, v75
	v_pk_fma_f32 v[60:61], v[60:61], v[78:79], v[80:81]
	v_pk_fma_f32 v[70:71], v[58:59], v[56:57], v[70:71]
	v_cvt_pk_bf16_f32 v56, v60, v61
	v_cvt_pk_bf16_f32 v57, v62, v63
	v_cvt_pk_bf16_f32 v58, v68, v69
	v_cvt_pk_bf16_f32 v59, v70, v71
	v_lshl_add_u64 v[60:61], s[88:89], 0, v[76:77]
	global_store_dwordx4 v[60:61], v[56:59], off
	v_lshl_add_u64 v[60:61], v[64:65], 0, v[120:121]
	v_lshlrev_b64 v[64:65], 1, v[60:61]
	v_lshl_add_u64 v[56:57], v[66:67], 0, v[122:123]
	v_lshl_add_u64 v[60:61], s[16:17], 0, v[64:65]
	s_waitcnt vmcnt(13)
	s_nop 1
	v_mov_b64_e32 v[56:57], v[176:177]
	v_mov_b64_e32 v[58:59], v[178:179]
	v_add_u32_e32 v214, 0xa0000, v213
	global_load_dwordx4 v[176:179], v214, s[16:17] offset:256
	s_nop 0
	s_waitcnt vmcnt(12)
	s_nop 1
	v_mov_b64_e32 v[60:61], v[180:181]
	v_mov_b64_e32 v[62:63], v[182:183]
	v_add_u32_e32 v214, 0x210000, v212
	global_load_dwordx4 v[180:183], v214, s[6:7]
	v_lshlrev_b32_e32 v66, 16, v56
	v_and_b32_e32 v67, 0xffff0000, v56
	v_lshlrev_b32_e32 v68, 16, v60
	v_and_b32_e32 v69, 0xffff0000, v60
	v_lshlrev_b32_e32 v56, 16, v57
	v_and_b32_e32 v57, 0xffff0000, v57
	v_lshlrev_b32_e32 v60, 16, v61
	v_and_b32_e32 v61, 0xffff0000, v61
	v_pk_fma_f32 v[54:55], v[54:55], v[56:57], v[60:61]
	v_lshlrev_b32_e32 v56, 16, v58
	v_and_b32_e32 v57, 0xffff0000, v58
	v_lshlrev_b32_e32 v60, 16, v62
	v_and_b32_e32 v61, 0xffff0000, v62
	v_pk_fma_f32 v[56:57], v[48:49], v[56:57], v[60:61]
	v_lshlrev_b32_e32 v48, 16, v59
	v_and_b32_e32 v49, 0xffff0000, v59
	v_lshlrev_b32_e32 v58, 16, v63
	v_and_b32_e32 v59, 0xffff0000, v63
	v_pk_fma_f32 v[52:53], v[52:53], v[66:67], v[68:69]
	v_pk_fma_f32 v[58:59], v[50:51], v[48:49], v[58:59]
	v_cvt_pk_bf16_f32 v48, v52, v53
	v_cvt_pk_bf16_f32 v49, v54, v55
	v_cvt_pk_bf16_f32 v50, v56, v57
	v_cvt_pk_bf16_f32 v51, v58, v59
	v_lshl_add_u64 v[52:53], s[88:89], 0, v[64:65]
	global_store_dwordx4 v[52:53], v[48:51], off
	s_nop 1
	v_add_u32_e32 v50, 0x90, v140
	v_ashrrev_i32_e32 v51, 31, v50
	v_lshlrev_b64 v[48:49], 11, v[50:51]
	v_lshl_add_u64 v[56:57], v[48:49], 0, v[138:139]
	v_mad_i64_i32 v[50:51], s[2:3], v50, s26, v[144:145]
	v_lshl_add_u64 v[50:51], v[50:51], 0, s[56:57]
	v_lshlrev_b64 v[60:61], 1, v[56:57]
	v_lshl_add_u64 v[52:53], v[50:51], 0, v[142:143]
	v_lshl_add_u64 v[56:57], s[16:17], 0, v[60:61]
	s_waitcnt vmcnt(13)
	s_nop 1
	v_mov_b64_e32 v[52:53], v[184:185]
	v_mov_b64_e32 v[54:55], v[186:187]
	v_add_u32_e32 v214, 0xb0000, v213
	global_load_dwordx4 v[184:187], v214, s[16:17]
	s_nop 0
	s_waitcnt vmcnt(12)
	s_nop 1
	v_mov_b64_e32 v[56:57], v[188:189]
	v_mov_b64_e32 v[58:59], v[190:191]
	v_add_u32_e32 v214, 0x210000, v212
	global_load_dwordx4 v[188:191], v214, s[6:7] offset:256
	v_lshlrev_b32_e32 v62, 16, v52
	v_and_b32_e32 v63, 0xffff0000, v52
	v_lshlrev_b32_e32 v64, 16, v56
	v_and_b32_e32 v65, 0xffff0000, v56
	v_lshlrev_b32_e32 v52, 16, v53
	v_and_b32_e32 v53, 0xffff0000, v53
	v_lshlrev_b32_e32 v56, 16, v57
	v_and_b32_e32 v57, 0xffff0000, v57
	v_pk_fma_f32 v[46:47], v[46:47], v[52:53], v[56:57]
	v_lshlrev_b32_e32 v52, 16, v54
	v_and_b32_e32 v53, 0xffff0000, v54
	v_lshlrev_b32_e32 v56, 16, v58
	v_and_b32_e32 v57, 0xffff0000, v58
	v_pk_fma_f32 v[52:53], v[40:41], v[52:53], v[56:57]
	v_lshlrev_b32_e32 v40, 16, v55
	v_and_b32_e32 v41, 0xffff0000, v55
	v_lshlrev_b32_e32 v54, 16, v59
	v_and_b32_e32 v55, 0xffff0000, v59
	v_pk_fma_f32 v[44:45], v[44:45], v[62:63], v[64:65]
	v_pk_fma_f32 v[54:55], v[42:43], v[40:41], v[54:55]
	v_cvt_pk_bf16_f32 v40, v44, v45
	v_cvt_pk_bf16_f32 v41, v46, v47
	v_cvt_pk_bf16_f32 v42, v52, v53
	v_cvt_pk_bf16_f32 v43, v54, v55
	v_lshl_add_u64 v[44:45], s[88:89], 0, v[60:61]
	global_store_dwordx4 v[44:45], v[40:43], off
	v_lshl_add_u64 v[44:45], v[48:49], 0, v[120:121]
	v_lshlrev_b64 v[48:49], 1, v[44:45]
	v_lshl_add_u64 v[40:41], v[50:51], 0, v[122:123]
	v_lshl_add_u64 v[44:45], s[16:17], 0, v[48:49]
	s_waitcnt vmcnt(13)
	s_nop 1
	v_mov_b64_e32 v[40:41], v[192:193]
	v_mov_b64_e32 v[42:43], v[194:195]
	v_add_u32_e32 v214, 0xb0000, v213
	global_load_dwordx4 v[192:195], v214, s[16:17] offset:256
	s_nop 0
	s_waitcnt vmcnt(12)
	s_nop 1
	v_mov_b64_e32 v[44:45], v[196:197]
	v_mov_b64_e32 v[46:47], v[198:199]
	v_lshlrev_b32_e32 v50, 16, v40
	v_and_b32_e32 v51, 0xffff0000, v40
	v_lshlrev_b32_e32 v52, 16, v44
	v_and_b32_e32 v53, 0xffff0000, v44
	v_lshlrev_b32_e32 v40, 16, v41
	v_and_b32_e32 v41, 0xffff0000, v41
	v_lshlrev_b32_e32 v44, 16, v45
	v_and_b32_e32 v45, 0xffff0000, v45
	v_pk_fma_f32 v[38:39], v[38:39], v[40:41], v[44:45]
	v_lshlrev_b32_e32 v40, 16, v42
	v_and_b32_e32 v41, 0xffff0000, v42
	v_lshlrev_b32_e32 v44, 16, v46
	v_and_b32_e32 v45, 0xffff0000, v46
	v_pk_fma_f32 v[40:41], v[32:33], v[40:41], v[44:45]
	v_lshlrev_b32_e32 v32, 16, v43
	v_and_b32_e32 v33, 0xffff0000, v43
	v_lshlrev_b32_e32 v42, 16, v47
	v_and_b32_e32 v43, 0xffff0000, v47
	v_pk_fma_f32 v[36:37], v[36:37], v[50:51], v[52:53]
	v_pk_fma_f32 v[42:43], v[34:35], v[32:33], v[42:43]
	v_cvt_pk_bf16_f32 v32, v36, v37
	v_cvt_pk_bf16_f32 v33, v38, v39
	v_cvt_pk_bf16_f32 v34, v40, v41
	v_cvt_pk_bf16_f32 v35, v42, v43
	v_lshl_add_u64 v[36:37], s[88:89], 0, v[48:49]
	global_store_dwordx4 v[36:37], v[32:35], off
	s_nop 1
	v_add_u32_e32 v34, 0xa0, v140
	v_ashrrev_i32_e32 v35, 31, v34
	v_lshlrev_b64 v[32:33], 11, v[34:35]
	v_lshl_add_u64 v[40:41], v[32:33], 0, v[138:139]
	v_mad_i64_i32 v[34:35], s[2:3], v34, s26, v[144:145]
	v_lshl_add_u64 v[34:35], v[34:35], 0, s[56:57]
	v_lshlrev_b64 v[44:45], 1, v[40:41]
	v_lshl_add_u64 v[36:37], v[34:35], 0, v[142:143]
	v_lshl_add_u64 v[40:41], s[16:17], 0, v[44:45]
	s_waitcnt vmcnt(12)
; __device__ __forceinline__ unsigned cvt_pk_bf16(float lo, float hi) { const f32x2_t v = {lo, hi}; const bf16x2_t b = __builtin_convertvector(v, bf16x2_t); return __builtin_bit_cast(unsigned, b); }
;     __device__ __forceinline__ void operator()(const Acc& acc, const Unit& u, int wr, int wc, int fr, int fq) const {
;     ...
; #pragma unroll
;         for (int ai = 0; ai < 2; ++ai)
; #pragma unroll
;             for (int m = 0; m < 4; ++m) {
;                 asm volatile("" ::: "memory");
;                 const int r = row0 + ai * HALF + m * 16;
; #pragma unroll
;                 for (int bj = 0; bj < 2; ++bj) {
;                     const int c = col0 + bj * HALF; const size_t off = (size_t)r * D + c;
;                     const u32x4 gw = *(const u32x4*)(gates + (size_t)r * 6144 + br * D + c);
;                     f32x4 v0, v1;
;                     v0[0] = acc[ai][bj][m][0][0] * bflo(gw.x); v0[1] = acc[ai][bj][m][0][1] * bfhi(gw.x); v0[2] = acc[ai][bj][m][0][2] * bflo(gw.y); v0[3] = acc[ai][bj][m][0][3] * bfhi(gw.y);
;                     v1[0] = acc[ai][bj][m][1][0] * bflo(gw.z); v1[1] = acc[ai][bj][m][1][1] * bfhi(gw.z); v1[2] = acc[ai][bj][m][1][2] * bflo(gw.w); v1[3] = acc[ai][bj][m][1][3] * bfhi(gw.w);
;                     if (br > 0) { const u32x4 ma = *(const u32x4*)(prev + off);
;                         v0[0] += bflo(ma.x); v0[1] += bfhi(ma.x); v0[2] += bflo(ma.y); v0[3] += bfhi(ma.y); v1[0] += bflo(ma.z); v1[1] += bfhi(ma.z); v1[2] += bflo(ma.w); v1[3] += bfhi(ma.w); }
;                     u32x4 w; w.x = cvt_pk_bf16(v0[0], v0[1]); w.y = cvt_pk_bf16(v0[2], v0[3]); w.z = cvt_pk_bf16(v1[0], v1[1]); w.w = cvt_pk_bf16(v1[2], v1[3]);
;                     *(u32x4*)(dst + off) = w;
;                 }
	s_nop 1
	v_mov_b64_e32 v[36:37], v[200:201]
	v_mov_b64_e32 v[38:39], v[202:203]
	s_nop 0
	s_waitcnt vmcnt(10)
	s_nop 1
	v_mov_b64_e32 v[40:41], v[204:205]
	v_mov_b64_e32 v[42:43], v[206:207]
	v_lshlrev_b32_e32 v46, 16, v36
	v_and_b32_e32 v47, 0xffff0000, v36
	v_lshlrev_b32_e32 v48, 16, v40
	v_and_b32_e32 v49, 0xffff0000, v40
	v_lshlrev_b32_e32 v36, 16, v37
	v_and_b32_e32 v37, 0xffff0000, v37
	v_lshlrev_b32_e32 v40, 16, v41
	v_and_b32_e32 v41, 0xffff0000, v41
	v_pk_fma_f32 v[30:31], v[30:31], v[36:37], v[40:41]
	v_lshlrev_b32_e32 v36, 16, v38
	v_and_b32_e32 v37, 0xffff0000, v38
	v_lshlrev_b32_e32 v40, 16, v42
	v_and_b32_e32 v41, 0xffff0000, v42
	v_pk_fma_f32 v[36:37], v[24:25], v[36:37], v[40:41]
	v_lshlrev_b32_e32 v24, 16, v39
	v_and_b32_e32 v25, 0xffff0000, v39
	v_lshlrev_b32_e32 v38, 16, v43
	v_and_b32_e32 v39, 0xffff0000, v43
	v_pk_fma_f32 v[28:29], v[28:29], v[46:47], v[48:49]
	v_pk_fma_f32 v[38:39], v[26:27], v[24:25], v[38:39]
	v_cvt_pk_bf16_f32 v24, v28, v29
	v_cvt_pk_bf16_f32 v25, v30, v31
	v_cvt_pk_bf16_f32 v26, v36, v37
	v_cvt_pk_bf16_f32 v27, v38, v39
	v_lshl_add_u64 v[28:29], s[88:89], 0, v[44:45]
	global_store_dwordx4 v[28:29], v[24:27], off
	v_lshl_add_u64 v[28:29], v[32:33], 0, v[120:121]
	v_lshlrev_b64 v[32:33], 1, v[28:29]
	v_lshl_add_u64 v[24:25], v[34:35], 0, v[122:123]
	v_lshl_add_u64 v[28:29], s[16:17], 0, v[32:33]
	s_waitcnt vmcnt(10)
	s_nop 1
	v_mov_b64_e32 v[24:25], v[208:209]
	v_mov_b64_e32 v[26:27], v[210:211]
	s_nop 0
	s_waitcnt vmcnt(8)
	s_nop 1
	v_mov_b64_e32 v[28:29], v[176:177]
	v_mov_b64_e32 v[30:31], v[178:179]
	v_lshlrev_b32_e32 v34, 16, v24
	v_and_b32_e32 v35, 0xffff0000, v24
	v_lshlrev_b32_e32 v36, 16, v28
	v_and_b32_e32 v37, 0xffff0000, v28
	v_lshlrev_b32_e32 v24, 16, v25
	v_and_b32_e32 v25, 0xffff0000, v25
	v_lshlrev_b32_e32 v28, 16, v29
	v_and_b32_e32 v29, 0xffff0000, v29
	v_pk_fma_f32 v[22:23], v[22:23], v[24:25], v[28:29]
	v_lshlrev_b32_e32 v24, 16, v26
	v_and_b32_e32 v25, 0xffff0000, v26
	v_lshlrev_b32_e32 v28, 16, v30
	v_and_b32_e32 v29, 0xffff0000, v30
	v_pk_fma_f32 v[24:25], v[16:17], v[24:25], v[28:29]
	v_lshlrev_b32_e32 v16, 16, v27
	v_and_b32_e32 v17, 0xffff0000, v27
	v_lshlrev_b32_e32 v26, 16, v31
	v_and_b32_e32 v27, 0xffff0000, v31
	v_pk_fma_f32 v[20:21], v[20:21], v[34:35], v[36:37]
	v_pk_fma_f32 v[26:27], v[18:19], v[16:17], v[26:27]
	v_cvt_pk_bf16_f32 v16, v20, v21
	v_cvt_pk_bf16_f32 v17, v22, v23
	v_cvt_pk_bf16_f32 v18, v24, v25
	v_cvt_pk_bf16_f32 v19, v26, v27
	v_lshl_add_u64 v[20:21], s[88:89], 0, v[32:33]
	global_store_dwordx4 v[20:21], v[16:19], off
	s_nop 1
	v_add_u32_e32 v18, 0xb0, v140
	v_ashrrev_i32_e32 v19, 31, v18
	v_lshlrev_b64 v[16:17], 11, v[18:19]
	v_lshl_add_u64 v[24:25], v[16:17], 0, v[138:139]
	v_mad_i64_i32 v[18:19], s[2:3], v18, s26, v[144:145]
	v_lshl_add_u64 v[18:19], v[18:19], 0, s[56:57]
	v_lshlrev_b64 v[28:29], 1, v[24:25]
	v_lshl_add_u64 v[20:21], v[18:19], 0, v[142:143]
	v_lshl_add_u64 v[24:25], s[16:17], 0, v[28:29]
	s_waitcnt vmcnt(8)
	s_nop 1
	v_mov_b64_e32 v[20:21], v[180:181]
	v_mov_b64_e32 v[22:23], v[182:183]
	s_nop 0
	s_waitcnt vmcnt(6)
	s_nop 1
	v_mov_b64_e32 v[24:25], v[184:185]
	v_mov_b64_e32 v[26:27], v[186:187]
	v_lshlrev_b32_e32 v30, 16, v20
	v_and_b32_e32 v31, 0xffff0000, v20
	v_lshlrev_b32_e32 v32, 16, v24
	v_and_b32_e32 v33, 0xffff0000, v24
	v_lshlrev_b32_e32 v20, 16, v21
	v_and_b32_e32 v21, 0xffff0000, v21
	v_lshlrev_b32_e32 v24, 16, v25
	v_and_b32_e32 v25, 0xffff0000, v25
	v_pk_fma_f32 v[14:15], v[14:15], v[20:21], v[24:25]
	v_lshlrev_b32_e32 v20, 16, v22
	v_and_b32_e32 v21, 0xffff0000, v22
	v_lshlrev_b32_e32 v24, 16, v26
	v_and_b32_e32 v25, 0xffff0000, v26
	v_pk_fma_f32 v[20:21], v[8:9], v[20:21], v[24:25]
	v_lshlrev_b32_e32 v8, 16, v23
	v_and_b32_e32 v9, 0xffff0000, v23
	v_lshlrev_b32_e32 v22, 16, v27
	v_and_b32_e32 v23, 0xffff0000, v27
	v_pk_fma_f32 v[12:13], v[12:13], v[30:31], v[32:33]
	v_pk_fma_f32 v[22:23], v[10:11], v[8:9], v[22:23]
	v_cvt_pk_bf16_f32 v8, v12, v13
	v_cvt_pk_bf16_f32 v9, v14, v15
	v_cvt_pk_bf16_f32 v10, v20, v21
	v_cvt_pk_bf16_f32 v11, v22, v23
	v_lshl_add_u64 v[12:13], s[88:89], 0, v[28:29]
	global_store_dwordx4 v[12:13], v[8:11], off
	v_lshl_add_u64 v[12:13], v[16:17], 0, v[120:121]
	v_lshlrev_b64 v[16:17], 1, v[12:13]
	v_lshl_add_u64 v[8:9], v[18:19], 0, v[122:123]
	v_lshl_add_u64 v[12:13], s[16:17], 0, v[16:17]
	s_waitcnt vmcnt(6)
	s_nop 1
	v_mov_b64_e32 v[8:9], v[188:189]
	v_mov_b64_e32 v[10:11], v[190:191]
	s_nop 0
	s_waitcnt vmcnt(4)
	s_nop 1
	v_mov_b64_e32 v[12:13], v[192:193]
	v_mov_b64_e32 v[14:15], v[194:195]
	v_lshlrev_b32_e32 v18, 16, v8
	v_and_b32_e32 v19, 0xffff0000, v8
	v_lshlrev_b32_e32 v20, 16, v12
	v_and_b32_e32 v21, 0xffff0000, v12
	v_lshlrev_b32_e32 v8, 16, v9
	v_and_b32_e32 v9, 0xffff0000, v9
	v_lshlrev_b32_e32 v12, 16, v13
	v_and_b32_e32 v13, 0xffff0000, v13
	v_pk_fma_f32 v[6:7], v[6:7], v[8:9], v[12:13]
	v_lshlrev_b32_e32 v8, 16, v10
	v_and_b32_e32 v9, 0xffff0000, v10
	v_lshlrev_b32_e32 v12, 16, v14
	v_and_b32_e32 v13, 0xffff0000, v14
	v_pk_fma_f32 v[8:9], v[0:1], v[8:9], v[12:13]
	v_lshlrev_b32_e32 v0, 16, v11
	v_and_b32_e32 v1, 0xffff0000, v11
	v_lshlrev_b32_e32 v10, 16, v15
	v_and_b32_e32 v11, 0xffff0000, v15
	v_pk_fma_f32 v[4:5], v[4:5], v[18:19], v[20:21]
	v_pk_fma_f32 v[10:11], v[2:3], v[0:1], v[10:11]
	v_cvt_pk_bf16_f32 v0, v4, v5
	v_cvt_pk_bf16_f32 v1, v6, v7
	v_cvt_pk_bf16_f32 v2, v8, v9
	v_cvt_pk_bf16_f32 v3, v10, v11
	v_lshl_add_u64 v[4:5], s[88:89], 0, v[16:17]
	global_store_dwordx4 v[4:5], v[0:3], off
	s_cbranch_vccnz .LBB0_179
	s_andn2_b64 vcc, exec, s[14:15]
	s_cbranch_vccnz .LBB0_178
	s_barrier
	s_branch .LBB0_178

; __device__ __forceinline__ unsigned cvt_pk_bf16(float lo, float hi) { const f32x2_t v = {lo, hi}; const bf16x2_t b = __builtin_convertvector(v, bf16x2_t); return __builtin_bit_cast(unsigned, b); }
;     __device__ __forceinline__ void operator()(const Acc& acc, const Unit& u, int wr, int wc, int fr, int fq) const {
;     ...
; #pragma unroll
;         for (int ai = 0; ai < 2; ++ai)
; #pragma unroll
;             for (int m = 0; m < 4; ++m) {
;                 asm volatile("" ::: "memory");
;                 const int r = row0 + ai * HALF + m * 16;
; #pragma unroll
;                 for (int bj = 0; bj < 2; ++bj) {
;                     const int c = col0 + bj * HALF; const size_t off = (size_t)r * D + c;
;                     const u32x4 gw = *(const u32x4*)(gates + (size_t)r * 6144 + br * D + c);
;                     f32x4 v0, v1;
;                     v0[0] = acc[ai][bj][m][0][0] * bflo(gw.x); v0[1] = acc[ai][bj][m][0][1] * bfhi(gw.x); v0[2] = acc[ai][bj][m][0][2] * bflo(gw.y); v0[3] = acc[ai][bj][m][0][3] * bfhi(gw.y);
;                     v1[0] = acc[ai][bj][m][1][0] * bflo(gw.z); v1[1] = acc[ai][bj][m][1][1] * bfhi(gw.z); v1[2] = acc[ai][bj][m][1][2] * bflo(gw.w); v1[3] = acc[ai][bj][m][1][3] * bfhi(gw.w);
;                     if (br > 0) { const u32x4 ma = *(const u32x4*)(prev + off);
;                         v0[0] += bflo(ma.x); v0[1] += bfhi(ma.x); v0[2] += bflo(ma.y); v0[3] += bfhi(ma.y); v1[0] += bflo(ma.z); v1[1] += bfhi(ma.z); v1[2] += bflo(ma.w); v1[3] += bfhi(ma.w); }
;                     u32x4 w; w.x = cvt_pk_bf16(v0[0], v0[1]); w.y = cvt_pk_bf16(v0[2], v0[3]); w.z = cvt_pk_bf16(v1[0], v1[1]); w.w = cvt_pk_bf16(v1[2], v1[3]);
;                     *(u32x4*)(dst + off) = w;
;                 }
.LBB0_214:
	v_lshl_add_u32 v140, s54, 8, v146
	v_lshl_or_b32 v138, s42, 8, v148
	v_ashrrev_i32_e32 v141, 31, v140
	v_lshlrev_b64 v[158:159], 11, v[140:141]
	v_ashrrev_i32_e32 v139, 31, v138
	v_mov_b64_e32 v[144:145], s[6:7]
	v_lshl_add_u64 v[154:155], v[158:159], 0, v[138:139]
	v_mad_i64_i32 v[142:143], s[2:3], v140, s26, v[144:145]
	v_lshl_add_u64 v[166:167], v[142:143], 0, s[58:59]
	v_lshlrev_b64 v[142:143], 1, v[138:139]
	v_lshlrev_b64 v[170:171], 1, v[154:155]
	v_lshl_add_u64 v[150:151], v[166:167], 0, v[142:143]
	v_lshl_add_u64 v[154:155], s[88:89], 0, v[170:171]
	v_subrev_u32_e32 v212, s6, v150
	v_subrev_u32_e32 v213, s88, v154
	global_load_dwordx4 v[176:179], v212, s[6:7]
	global_load_dwordx4 v[180:183], v213, s[88:89]
	global_load_dwordx4 v[184:187], v212, s[6:7] offset:256
	global_load_dwordx4 v[188:191], v213, s[88:89] offset:256
	v_add_u32_e32 v214, 0x30000, v212
	global_load_dwordx4 v[192:195], v214, s[6:7]
	v_add_u32_e32 v214, 0x10000, v213
	global_load_dwordx4 v[196:199], v214, s[88:89]
	v_add_u32_e32 v214, 0x30000, v212
	global_load_dwordx4 v[200:203], v214, s[6:7] offset:256
	v_add_u32_e32 v214, 0x10000, v213
	global_load_dwordx4 v[204:207], v214, s[88:89] offset:256
	v_add_u32_e32 v214, 0x60000, v212
	global_load_dwordx4 v[208:211], v214, s[6:7]
	s_waitcnt vmcnt(8)
	s_nop 1
	v_mov_b64_e32 v[150:151], v[176:177]
	v_mov_b64_e32 v[152:153], v[178:179]
	v_add_u32_e32 v214, 0x20000, v213
	global_load_dwordx4 v[176:179], v214, s[88:89]
	s_mov_b64 s[24:25], -1
	s_waitcnt vmcnt(8)
	s_nop 1
	v_mov_b64_e32 v[154:155], v[180:181]
	v_mov_b64_e32 v[156:157], v[182:183]
	v_add_u32_e32 v214, 0x60000, v212
	global_load_dwordx4 v[180:183], v214, s[6:7] offset:256
	s_andn2_b64 vcc, exec, s[4:5]
	v_lshlrev_b32_e32 v172, 16, v150
	v_and_b32_e32 v173, 0xffff0000, v150
	v_lshlrev_b32_e32 v174, 16, v154
	v_and_b32_e32 v175, 0xffff0000, v154
	v_lshlrev_b32_e32 v150, 16, v151
	v_and_b32_e32 v151, 0xffff0000, v151
	v_lshlrev_b32_e32 v154, 16, v155
	v_and_b32_e32 v155, 0xffff0000, v155
	v_pk_fma_f32 v[126:127], v[126:127], v[150:151], v[154:155]
	v_lshlrev_b32_e32 v150, 16, v152
	v_and_b32_e32 v151, 0xffff0000, v152
	v_lshlrev_b32_e32 v154, 16, v156
	v_and_b32_e32 v155, 0xffff0000, v156
	v_pk_fma_f32 v[150:151], v[120:121], v[150:151], v[154:155]
	v_lshlrev_b32_e32 v120, 16, v153
	v_and_b32_e32 v121, 0xffff0000, v153
	v_lshlrev_b32_e32 v152, 16, v157
	v_and_b32_e32 v153, 0xffff0000, v157
	v_pk_fma_f32 v[124:125], v[124:125], v[172:173], v[174:175]
	v_pk_fma_f32 v[152:153], v[122:123], v[120:121], v[152:153]
	v_cvt_pk_bf16_f32 v120, v124, v125
	v_cvt_pk_bf16_f32 v121, v126, v127
	v_cvt_pk_bf16_f32 v122, v150, v151
	v_cvt_pk_bf16_f32 v123, v152, v153
	v_lshl_add_u64 v[124:125], s[8:9], 0, v[170:171]
	global_store_dwordx4 v[124:125], v[120:123], off
	s_nop 1
	v_or_b32_e32 v120, 0x80, v138
	v_ashrrev_i32_e32 v121, 31, v120
	v_lshl_add_u64 v[150:151], v[158:159], 0, v[120:121]
	v_lshlrev_b64 v[122:123], 1, v[120:121]
	v_lshlrev_b64 v[154:155], 1, v[150:151]
	v_lshl_add_u64 v[124:125], v[166:167], 0, v[122:123]
	v_lshl_add_u64 v[150:151], s[88:89], 0, v[154:155]
	s_waitcnt vmcnt(9)
	s_nop 1
	v_mov_b64_e32 v[124:125], v[184:185]
	v_mov_b64_e32 v[126:127], v[186:187]
	v_add_u32_e32 v214, 0x20000, v213
	global_load_dwordx4 v[184:187], v214, s[88:89] offset:256
	s_nop 0
	s_waitcnt vmcnt(9)
	s_nop 1
	v_mov_b64_e32 v[150:151], v[188:189]
	v_mov_b64_e32 v[152:153], v[190:191]
	v_add_u32_e32 v214, 0x90000, v212
	global_load_dwordx4 v[188:191], v214, s[6:7]
	v_lshlrev_b32_e32 v156, 16, v124
	v_and_b32_e32 v157, 0xffff0000, v124
	v_lshlrev_b32_e32 v158, 16, v150
	v_and_b32_e32 v159, 0xffff0000, v150
	v_lshlrev_b32_e32 v124, 16, v125
	v_and_b32_e32 v125, 0xffff0000, v125
	v_lshlrev_b32_e32 v150, 16, v151
	v_and_b32_e32 v151, 0xffff0000, v151
	v_pk_fma_f32 v[118:119], v[118:119], v[124:125], v[150:151]
	v_lshlrev_b32_e32 v124, 16, v126
	v_and_b32_e32 v125, 0xffff0000, v126
	v_lshlrev_b32_e32 v150, 16, v152
	v_and_b32_e32 v151, 0xffff0000, v152
	v_pk_fma_f32 v[124:125], v[112:113], v[124:125], v[150:151]
	v_lshlrev_b32_e32 v112, 16, v127
	v_and_b32_e32 v113, 0xffff0000, v127
	v_lshlrev_b32_e32 v126, 16, v153
	v_and_b32_e32 v127, 0xffff0000, v153
	v_pk_fma_f32 v[116:117], v[116:117], v[156:157], v[158:159]
	v_pk_fma_f32 v[126:127], v[114:115], v[112:113], v[126:127]
	v_cvt_pk_bf16_f32 v112, v116, v117
	v_cvt_pk_bf16_f32 v113, v118, v119
	v_cvt_pk_bf16_f32 v114, v124, v125
	v_cvt_pk_bf16_f32 v115, v126, v127
	v_lshl_add_u64 v[116:117], s[8:9], 0, v[154:155]
	global_store_dwordx4 v[116:117], v[112:115], off
	s_nop 1
	v_or_b32_e32 v114, 16, v140
	v_ashrrev_i32_e32 v115, 31, v114
	v_lshlrev_b64 v[112:113], 11, v[114:115]
	v_lshl_add_u64 v[124:125], v[112:113], 0, v[138:139]
	v_mad_i64_i32 v[114:115], s[2:3], v114, s26, v[144:145]
	v_lshl_add_u64 v[114:115], v[114:115], 0, s[58:59]
	v_lshlrev_b64 v[150:151], 1, v[124:125]
	v_lshl_add_u64 v[116:117], v[114:115], 0, v[142:143]
	v_lshl_add_u64 v[124:125], s[88:89], 0, v[150:151]
	s_waitcnt vmcnt(10)
	s_nop 1
	v_mov_b64_e32 v[116:117], v[192:193]
	v_mov_b64_e32 v[118:119], v[194:195]
	v_add_u32_e32 v214, 0x30000, v213
	global_load_dwordx4 v[192:195], v214, s[88:89]
	s_nop 0
	s_waitcnt vmcnt(10)
; __device__ __forceinline__ unsigned cvt_pk_bf16(float lo, float hi) { const f32x2_t v = {lo, hi}; const bf16x2_t b = __builtin_convertvector(v, bf16x2_t); return __builtin_bit_cast(unsigned, b); }
;     __device__ __forceinline__ void operator()(const Acc& acc, const Unit& u, int wr, int wc, int fr, int fq) const {
;     ...
; #pragma unroll
;         for (int ai = 0; ai < 2; ++ai)
; #pragma unroll
;             for (int m = 0; m < 4; ++m) {
;                 asm volatile("" ::: "memory");
;                 const int r = row0 + ai * HALF + m * 16;
; #pragma unroll
;                 for (int bj = 0; bj < 2; ++bj) {
;                     const int c = col0 + bj * HALF; const size_t off = (size_t)r * D + c;
;                     const u32x4 gw = *(const u32x4*)(gates + (size_t)r * 6144 + br * D + c);
;                     f32x4 v0, v1;
;                     v0[0] = acc[ai][bj][m][0][0] * bflo(gw.x); v0[1] = acc[ai][bj][m][0][1] * bfhi(gw.x); v0[2] = acc[ai][bj][m][0][2] * bflo(gw.y); v0[3] = acc[ai][bj][m][0][3] * bfhi(gw.y);
;                     v1[0] = acc[ai][bj][m][1][0] * bflo(gw.z); v1[1] = acc[ai][bj][m][1][1] * bfhi(gw.z); v1[2] = acc[ai][bj][m][1][2] * bflo(gw.w); v1[3] = acc[ai][bj][m][1][3] * bfhi(gw.w);
;                     if (br > 0) { const u32x4 ma = *(const u32x4*)(prev + off);
;                         v0[0] += bflo(ma.x); v0[1] += bfhi(ma.x); v0[2] += bflo(ma.y); v0[3] += bfhi(ma.y); v1[0] += bflo(ma.z); v1[1] += bfhi(ma.z); v1[2] += bflo(ma.w); v1[3] += bfhi(ma.w); }
;                     u32x4 w; w.x = cvt_pk_bf16(v0[0], v0[1]); w.y = cvt_pk_bf16(v0[2], v0[3]); w.z = cvt_pk_bf16(v1[0], v1[1]); w.w = cvt_pk_bf16(v1[2], v1[3]);
;                     *(u32x4*)(dst + off) = w;
;                 }
	s_nop 1
	v_mov_b64_e32 v[124:125], v[196:197]
	v_mov_b64_e32 v[126:127], v[198:199]
	v_add_u32_e32 v214, 0x90000, v212
	global_load_dwordx4 v[196:199], v214, s[6:7] offset:256
	v_lshlrev_b32_e32 v152, 16, v116
	v_and_b32_e32 v153, 0xffff0000, v116
	v_lshlrev_b32_e32 v154, 16, v124
	v_and_b32_e32 v155, 0xffff0000, v124
	v_lshlrev_b32_e32 v116, 16, v117
	v_and_b32_e32 v117, 0xffff0000, v117
	v_lshlrev_b32_e32 v124, 16, v125
	v_and_b32_e32 v125, 0xffff0000, v125
	v_pk_fma_f32 v[110:111], v[110:111], v[116:117], v[124:125]
	v_lshlrev_b32_e32 v116, 16, v118
	v_and_b32_e32 v117, 0xffff0000, v118
	v_lshlrev_b32_e32 v124, 16, v126
	v_and_b32_e32 v125, 0xffff0000, v126
	v_pk_fma_f32 v[116:117], v[104:105], v[116:117], v[124:125]
	v_lshlrev_b32_e32 v104, 16, v119
	v_and_b32_e32 v105, 0xffff0000, v119
	v_lshlrev_b32_e32 v118, 16, v127
	v_and_b32_e32 v119, 0xffff0000, v127
	v_pk_fma_f32 v[108:109], v[108:109], v[152:153], v[154:155]
	v_pk_fma_f32 v[118:119], v[106:107], v[104:105], v[118:119]
	v_cvt_pk_bf16_f32 v104, v108, v109
	v_cvt_pk_bf16_f32 v105, v110, v111
	v_cvt_pk_bf16_f32 v106, v116, v117
	v_cvt_pk_bf16_f32 v107, v118, v119
	v_lshl_add_u64 v[108:109], s[8:9], 0, v[150:151]
	global_store_dwordx4 v[108:109], v[104:107], off
	v_lshl_add_u64 v[108:109], v[112:113], 0, v[120:121]
	v_lshlrev_b64 v[112:113], 1, v[108:109]
	v_lshl_add_u64 v[104:105], v[114:115], 0, v[122:123]
	v_lshl_add_u64 v[108:109], s[88:89], 0, v[112:113]
	s_waitcnt vmcnt(11)
	s_nop 1
	v_mov_b64_e32 v[104:105], v[200:201]
	v_mov_b64_e32 v[106:107], v[202:203]
	v_add_u32_e32 v214, 0x30000, v213
	global_load_dwordx4 v[200:203], v214, s[88:89] offset:256
	s_nop 0
	s_waitcnt vmcnt(11)
	s_nop 1
	v_mov_b64_e32 v[108:109], v[204:205]
	v_mov_b64_e32 v[110:111], v[206:207]
	v_add_u32_e32 v214, 0x180000, v212
	global_load_dwordx4 v[204:207], v214, s[6:7]
	v_lshlrev_b32_e32 v114, 16, v104
	v_and_b32_e32 v115, 0xffff0000, v104
	v_lshlrev_b32_e32 v116, 16, v108
	v_and_b32_e32 v117, 0xffff0000, v108
	v_lshlrev_b32_e32 v104, 16, v105
	v_and_b32_e32 v105, 0xffff0000, v105
	v_lshlrev_b32_e32 v108, 16, v109
	v_and_b32_e32 v109, 0xffff0000, v109
	v_pk_fma_f32 v[102:103], v[102:103], v[104:105], v[108:109]
	v_lshlrev_b32_e32 v104, 16, v106
	v_and_b32_e32 v105, 0xffff0000, v106
	v_lshlrev_b32_e32 v108, 16, v110
	v_and_b32_e32 v109, 0xffff0000, v110
	v_pk_fma_f32 v[104:105], v[96:97], v[104:105], v[108:109]
	v_lshlrev_b32_e32 v96, 16, v107
	v_and_b32_e32 v97, 0xffff0000, v107
	v_lshlrev_b32_e32 v106, 16, v111
	v_and_b32_e32 v107, 0xffff0000, v111
	v_pk_fma_f32 v[100:101], v[100:101], v[114:115], v[116:117]
	v_pk_fma_f32 v[106:107], v[98:99], v[96:97], v[106:107]
	v_cvt_pk_bf16_f32 v96, v100, v101
	v_cvt_pk_bf16_f32 v97, v102, v103
	v_cvt_pk_bf16_f32 v98, v104, v105
	v_cvt_pk_bf16_f32 v99, v106, v107
	v_lshl_add_u64 v[100:101], s[8:9], 0, v[112:113]
	global_store_dwordx4 v[100:101], v[96:99], off
	s_nop 1
	v_or_b32_e32 v98, 32, v140
	v_ashrrev_i32_e32 v99, 31, v98
	v_lshlrev_b64 v[96:97], 11, v[98:99]
	v_lshl_add_u64 v[104:105], v[96:97], 0, v[138:139]
	v_mad_i64_i32 v[98:99], s[2:3], v98, s26, v[144:145]
	v_lshl_add_u64 v[98:99], v[98:99], 0, s[58:59]
	v_lshlrev_b64 v[108:109], 1, v[104:105]
	v_lshl_add_u64 v[100:101], v[98:99], 0, v[142:143]
	v_lshl_add_u64 v[104:105], s[88:89], 0, v[108:109]
	s_waitcnt vmcnt(12)
	s_nop 1
	v_mov_b64_e32 v[100:101], v[208:209]
	v_mov_b64_e32 v[102:103], v[210:211]
	v_add_u32_e32 v214, 0x80000, v213
	global_load_dwordx4 v[208:211], v214, s[88:89]
	s_nop 0
	s_waitcnt vmcnt(12)
	s_nop 1
	v_mov_b64_e32 v[104:105], v[176:177]
	v_mov_b64_e32 v[106:107], v[178:179]
	v_add_u32_e32 v214, 0x180000, v212
	global_load_dwordx4 v[176:179], v214, s[6:7] offset:256
	v_lshlrev_b32_e32 v110, 16, v100
	v_and_b32_e32 v111, 0xffff0000, v100
	v_lshlrev_b32_e32 v112, 16, v104
	v_and_b32_e32 v113, 0xffff0000, v104
	v_lshlrev_b32_e32 v100, 16, v101
	v_and_b32_e32 v101, 0xffff0000, v101
	v_lshlrev_b32_e32 v104, 16, v105
	v_and_b32_e32 v105, 0xffff0000, v105
	v_pk_fma_f32 v[94:95], v[94:95], v[100:101], v[104:105]
	v_lshlrev_b32_e32 v100, 16, v102
	v_and_b32_e32 v101, 0xffff0000, v102
	v_lshlrev_b32_e32 v104, 16, v106
	v_and_b32_e32 v105, 0xffff0000, v106
	v_pk_fma_f32 v[100:101], v[88:89], v[100:101], v[104:105]
	v_lshlrev_b32_e32 v88, 16, v103
	v_and_b32_e32 v89, 0xffff0000, v103
	v_lshlrev_b32_e32 v102, 16, v107
	v_and_b32_e32 v103, 0xffff0000, v107
	v_pk_fma_f32 v[92:93], v[92:93], v[110:111], v[112:113]
	v_pk_fma_f32 v[102:103], v[90:91], v[88:89], v[102:103]
	v_cvt_pk_bf16_f32 v88, v92, v93
	v_cvt_pk_bf16_f32 v89, v94, v95
	v_cvt_pk_bf16_f32 v90, v100, v101
	v_cvt_pk_bf16_f32 v91, v102, v103
	v_lshl_add_u64 v[92:93], s[8:9], 0, v[108:109]
	global_store_dwordx4 v[92:93], v[88:91], off
	v_lshl_add_u64 v[92:93], v[96:97], 0, v[120:121]
	v_lshlrev_b64 v[96:97], 1, v[92:93]
	v_lshl_add_u64 v[88:89], v[98:99], 0, v[122:123]
	v_lshl_add_u64 v[92:93], s[88:89], 0, v[96:97]
	s_waitcnt vmcnt(13)
	s_nop 1
	v_mov_b64_e32 v[88:89], v[180:181]
	v_mov_b64_e32 v[90:91], v[182:183]
	v_add_u32_e32 v214, 0x80000, v213
	global_load_dwordx4 v[180:183], v214, s[88:89] offset:256
	s_nop 0
	s_waitcnt vmcnt(12)
; __device__ __forceinline__ unsigned cvt_pk_bf16(float lo, float hi) { const f32x2_t v = {lo, hi}; const bf16x2_t b = __builtin_convertvector(v, bf16x2_t); return __builtin_bit_cast(unsigned, b); }
;     __device__ __forceinline__ void operator()(const Acc& acc, const Unit& u, int wr, int wc, int fr, int fq) const {
;     ...
; #pragma unroll
;         for (int ai = 0; ai < 2; ++ai)
; #pragma unroll
;             for (int m = 0; m < 4; ++m) {
;                 asm volatile("" ::: "memory");
;                 const int r = row0 + ai * HALF + m * 16;
; #pragma unroll
;                 for (int bj = 0; bj < 2; ++bj) {
;                     const int c = col0 + bj * HALF; const size_t off = (size_t)r * D + c;
;                     const u32x4 gw = *(const u32x4*)(gates + (size_t)r * 6144 + br * D + c);
;                     f32x4 v0, v1;
;                     v0[0] = acc[ai][bj][m][0][0] * bflo(gw.x); v0[1] = acc[ai][bj][m][0][1] * bfhi(gw.x); v0[2] = acc[ai][bj][m][0][2] * bflo(gw.y); v0[3] = acc[ai][bj][m][0][3] * bfhi(gw.y);
;                     v1[0] = acc[ai][bj][m][1][0] * bflo(gw.z); v1[1] = acc[ai][bj][m][1][1] * bfhi(gw.z); v1[2] = acc[ai][bj][m][1][2] * bflo(gw.w); v1[3] = acc[ai][bj][m][1][3] * bfhi(gw.w);
;                     if (br > 0) { const u32x4 ma = *(const u32x4*)(prev + off);
;                         v0[0] += bflo(ma.x); v0[1] += bfhi(ma.x); v0[2] += bflo(ma.y); v0[3] += bfhi(ma.y); v1[0] += bflo(ma.z); v1[1] += bfhi(ma.z); v1[2] += bflo(ma.w); v1[3] += bfhi(ma.w); }
;                     u32x4 w; w.x = cvt_pk_bf16(v0[0], v0[1]); w.y = cvt_pk_bf16(v0[2], v0[3]); w.z = cvt_pk_bf16(v1[0], v1[1]); w.w = cvt_pk_bf16(v1[2], v1[3]);
;                     *(u32x4*)(dst + off) = w;
;                 }
	s_nop 1
	v_mov_b64_e32 v[92:93], v[184:185]
	v_mov_b64_e32 v[94:95], v[186:187]
	v_add_u32_e32 v214, 0x1b0000, v212
	global_load_dwordx4 v[184:187], v214, s[6:7]
	v_lshlrev_b32_e32 v98, 16, v88
	v_and_b32_e32 v99, 0xffff0000, v88
	v_lshlrev_b32_e32 v100, 16, v92
	v_and_b32_e32 v101, 0xffff0000, v92
	v_lshlrev_b32_e32 v88, 16, v89
	v_and_b32_e32 v89, 0xffff0000, v89
	v_lshlrev_b32_e32 v92, 16, v93
	v_and_b32_e32 v93, 0xffff0000, v93
	v_pk_fma_f32 v[86:87], v[86:87], v[88:89], v[92:93]
	v_lshlrev_b32_e32 v88, 16, v90
	v_and_b32_e32 v89, 0xffff0000, v90
	v_lshlrev_b32_e32 v92, 16, v94
	v_and_b32_e32 v93, 0xffff0000, v94
	v_pk_fma_f32 v[88:89], v[80:81], v[88:89], v[92:93]
	v_lshlrev_b32_e32 v80, 16, v91
	v_and_b32_e32 v81, 0xffff0000, v91
	v_lshlrev_b32_e32 v90, 16, v95
	v_and_b32_e32 v91, 0xffff0000, v95
	v_pk_fma_f32 v[84:85], v[84:85], v[98:99], v[100:101]
	v_pk_fma_f32 v[90:91], v[82:83], v[80:81], v[90:91]
	v_cvt_pk_bf16_f32 v80, v84, v85
	v_cvt_pk_bf16_f32 v81, v86, v87
	v_cvt_pk_bf16_f32 v82, v88, v89
	v_cvt_pk_bf16_f32 v83, v90, v91
	v_lshl_add_u64 v[84:85], s[8:9], 0, v[96:97]
	global_store_dwordx4 v[84:85], v[80:83], off
	s_nop 1
	v_or_b32_e32 v82, 48, v140
	v_ashrrev_i32_e32 v83, 31, v82
	v_lshlrev_b64 v[80:81], 11, v[82:83]
	v_lshl_add_u64 v[88:89], v[80:81], 0, v[138:139]
	v_mad_i64_i32 v[82:83], s[2:3], v82, s26, v[144:145]
	v_lshl_add_u64 v[82:83], v[82:83], 0, s[58:59]
	v_lshlrev_b64 v[92:93], 1, v[88:89]
	v_lshl_add_u64 v[84:85], v[82:83], 0, v[142:143]
	v_lshl_add_u64 v[88:89], s[88:89], 0, v[92:93]
	s_waitcnt vmcnt(13)
	s_nop 1
	v_mov_b64_e32 v[84:85], v[188:189]
	v_mov_b64_e32 v[86:87], v[190:191]
	v_add_u32_e32 v214, 0x90000, v213
	global_load_dwordx4 v[188:191], v214, s[88:89]
	s_nop 0
	s_waitcnt vmcnt(12)
	s_nop 1
	v_mov_b64_e32 v[88:89], v[192:193]
	v_mov_b64_e32 v[90:91], v[194:195]
	v_add_u32_e32 v214, 0x1b0000, v212
	global_load_dwordx4 v[192:195], v214, s[6:7] offset:256
	v_lshlrev_b32_e32 v94, 16, v84
	v_and_b32_e32 v95, 0xffff0000, v84
	v_lshlrev_b32_e32 v96, 16, v88
	v_and_b32_e32 v97, 0xffff0000, v88
	v_lshlrev_b32_e32 v84, 16, v85
	v_and_b32_e32 v85, 0xffff0000, v85
	v_lshlrev_b32_e32 v88, 16, v89
	v_and_b32_e32 v89, 0xffff0000, v89
	v_pk_fma_f32 v[78:79], v[78:79], v[84:85], v[88:89]
	v_lshlrev_b32_e32 v84, 16, v86
	v_and_b32_e32 v85, 0xffff0000, v86
	v_lshlrev_b32_e32 v88, 16, v90
	v_and_b32_e32 v89, 0xffff0000, v90
	v_pk_fma_f32 v[84:85], v[72:73], v[84:85], v[88:89]
	v_lshlrev_b32_e32 v72, 16, v87
	v_and_b32_e32 v73, 0xffff0000, v87
	v_lshlrev_b32_e32 v86, 16, v91
	v_and_b32_e32 v87, 0xffff0000, v91
	v_pk_fma_f32 v[76:77], v[76:77], v[94:95], v[96:97]
	v_pk_fma_f32 v[86:87], v[74:75], v[72:73], v[86:87]
	v_cvt_pk_bf16_f32 v72, v76, v77
	v_cvt_pk_bf16_f32 v73, v78, v79
	v_cvt_pk_bf16_f32 v74, v84, v85
	v_cvt_pk_bf16_f32 v75, v86, v87
	v_lshl_add_u64 v[76:77], s[8:9], 0, v[92:93]
	global_store_dwordx4 v[76:77], v[72:75], off
	v_lshl_add_u64 v[76:77], v[80:81], 0, v[120:121]
	v_lshlrev_b64 v[80:81], 1, v[76:77]
	v_lshl_add_u64 v[72:73], v[82:83], 0, v[122:123]
	v_lshl_add_u64 v[76:77], s[88:89], 0, v[80:81]
	s_waitcnt vmcnt(13)
	s_nop 1
	v_mov_b64_e32 v[72:73], v[196:197]
	v_mov_b64_e32 v[74:75], v[198:199]
	v_add_u32_e32 v214, 0x90000, v213
	global_load_dwordx4 v[196:199], v214, s[88:89] offset:256
	s_nop 0
	s_waitcnt vmcnt(12)
	s_nop 1
	v_mov_b64_e32 v[76:77], v[200:201]
	v_mov_b64_e32 v[78:79], v[202:203]
	v_add_u32_e32 v214, 0x1e0000, v212
	global_load_dwordx4 v[200:203], v214, s[6:7]
	v_lshlrev_b32_e32 v82, 16, v72
	v_and_b32_e32 v83, 0xffff0000, v72
	v_lshlrev_b32_e32 v84, 16, v76
	v_and_b32_e32 v85, 0xffff0000, v76
	v_lshlrev_b32_e32 v72, 16, v73
	v_and_b32_e32 v73, 0xffff0000, v73
	v_lshlrev_b32_e32 v76, 16, v77
	v_and_b32_e32 v77, 0xffff0000, v77
	v_pk_fma_f32 v[70:71], v[70:71], v[72:73], v[76:77]
	v_lshlrev_b32_e32 v72, 16, v74
	v_and_b32_e32 v73, 0xffff0000, v74
	v_lshlrev_b32_e32 v76, 16, v78
	v_and_b32_e32 v77, 0xffff0000, v78
	v_pk_fma_f32 v[72:73], v[64:65], v[72:73], v[76:77]
	v_lshlrev_b32_e32 v64, 16, v75
	v_and_b32_e32 v65, 0xffff0000, v75
	v_lshlrev_b32_e32 v74, 16, v79
	v_and_b32_e32 v75, 0xffff0000, v79
	v_pk_fma_f32 v[68:69], v[68:69], v[82:83], v[84:85]
	v_pk_fma_f32 v[74:75], v[66:67], v[64:65], v[74:75]
	v_cvt_pk_bf16_f32 v64, v68, v69
	v_cvt_pk_bf16_f32 v65, v70, v71
	v_cvt_pk_bf16_f32 v66, v72, v73
	v_cvt_pk_bf16_f32 v67, v74, v75
	v_lshl_add_u64 v[68:69], s[8:9], 0, v[80:81]
	global_store_dwordx4 v[68:69], v[64:67], off
	s_nop 1
	v_add_u32_e32 v66, 0x80, v140
	v_ashrrev_i32_e32 v67, 31, v66
	v_lshlrev_b64 v[64:65], 11, v[66:67]
	v_lshl_add_u64 v[72:73], v[64:65], 0, v[138:139]
	v_mad_i64_i32 v[66:67], s[2:3], v66, s26, v[144:145]
	v_lshl_add_u64 v[66:67], v[66:67], 0, s[58:59]
	v_lshlrev_b64 v[76:77], 1, v[72:73]
	v_lshl_add_u64 v[68:69], v[66:67], 0, v[142:143]
	v_lshl_add_u64 v[72:73], s[88:89], 0, v[76:77]
	s_waitcnt vmcnt(13)
	s_nop 1
	v_mov_b64_e32 v[68:69], v[204:205]
	v_mov_b64_e32 v[70:71], v[206:207]
	v_add_u32_e32 v214, 0xa0000, v213
	global_load_dwordx4 v[204:207], v214, s[88:89]
	s_nop 0
	s_waitcnt vmcnt(12)
; __device__ __forceinline__ unsigned cvt_pk_bf16(float lo, float hi) { const f32x2_t v = {lo, hi}; const bf16x2_t b = __builtin_convertvector(v, bf16x2_t); return __builtin_bit_cast(unsigned, b); }
;     __device__ __forceinline__ void operator()(const Acc& acc, const Unit& u, int wr, int wc, int fr, int fq) const {
;     ...
; #pragma unroll
;         for (int ai = 0; ai < 2; ++ai)
; #pragma unroll
;             for (int m = 0; m < 4; ++m) {
;                 asm volatile("" ::: "memory");
;                 const int r = row0 + ai * HALF + m * 16;
; #pragma unroll
;                 for (int bj = 0; bj < 2; ++bj) {
;                     const int c = col0 + bj * HALF; const size_t off = (size_t)r * D + c;
;                     const u32x4 gw = *(const u32x4*)(gates + (size_t)r * 6144 + br * D + c);
;                     f32x4 v0, v1;
;                     v0[0] = acc[ai][bj][m][0][0] * bflo(gw.x); v0[1] = acc[ai][bj][m][0][1] * bfhi(gw.x); v0[2] = acc[ai][bj][m][0][2] * bflo(gw.y); v0[3] = acc[ai][bj][m][0][3] * bfhi(gw.y);
;                     v1[0] = acc[ai][bj][m][1][0] * bflo(gw.z); v1[1] = acc[ai][bj][m][1][1] * bfhi(gw.z); v1[2] = acc[ai][bj][m][1][2] * bflo(gw.w); v1[3] = acc[ai][bj][m][1][3] * bfhi(gw.w);
;                     if (br > 0) { const u32x4 ma = *(const u32x4*)(prev + off);
;                         v0[0] += bflo(ma.x); v0[1] += bfhi(ma.x); v0[2] += bflo(ma.y); v0[3] += bfhi(ma.y); v1[0] += bflo(ma.z); v1[1] += bfhi(ma.z); v1[2] += bflo(ma.w); v1[3] += bfhi(ma.w); }
;                     u32x4 w; w.x = cvt_pk_bf16(v0[0], v0[1]); w.y = cvt_pk_bf16(v0[2], v0[3]); w.z = cvt_pk_bf16(v1[0], v1[1]); w.w = cvt_pk_bf16(v1[2], v1[3]);
;                     *(u32x4*)(dst + off) = w;
;                 }
	s_nop 1
	v_mov_b64_e32 v[72:73], v[208:209]
	v_mov_b64_e32 v[74:75], v[210:211]
	v_add_u32_e32 v214, 0x1e0000, v212
	global_load_dwordx4 v[208:211], v214, s[6:7] offset:256
	v_lshlrev_b32_e32 v78, 16, v68
	v_and_b32_e32 v79, 0xffff0000, v68
	v_lshlrev_b32_e32 v80, 16, v72
	v_and_b32_e32 v81, 0xffff0000, v72
	v_lshlrev_b32_e32 v68, 16, v69
	v_and_b32_e32 v69, 0xffff0000, v69
	v_lshlrev_b32_e32 v72, 16, v73
	v_and_b32_e32 v73, 0xffff0000, v73
	v_pk_fma_f32 v[62:63], v[62:63], v[68:69], v[72:73]
	v_lshlrev_b32_e32 v68, 16, v70
	v_and_b32_e32 v69, 0xffff0000, v70
	v_lshlrev_b32_e32 v72, 16, v74
	v_and_b32_e32 v73, 0xffff0000, v74
	v_pk_fma_f32 v[68:69], v[56:57], v[68:69], v[72:73]
	v_lshlrev_b32_e32 v56, 16, v71
	v_and_b32_e32 v57, 0xffff0000, v71
	v_lshlrev_b32_e32 v70, 16, v75
	v_and_b32_e32 v71, 0xffff0000, v75
	v_pk_fma_f32 v[60:61], v[60:61], v[78:79], v[80:81]
	v_pk_fma_f32 v[70:71], v[58:59], v[56:57], v[70:71]
	v_cvt_pk_bf16_f32 v56, v60, v61
	v_cvt_pk_bf16_f32 v57, v62, v63
	v_cvt_pk_bf16_f32 v58, v68, v69
	v_cvt_pk_bf16_f32 v59, v70, v71
	v_lshl_add_u64 v[60:61], s[8:9], 0, v[76:77]
	global_store_dwordx4 v[60:61], v[56:59], off
	v_lshl_add_u64 v[60:61], v[64:65], 0, v[120:121]
	v_lshlrev_b64 v[64:65], 1, v[60:61]
	v_lshl_add_u64 v[56:57], v[66:67], 0, v[122:123]
	v_lshl_add_u64 v[60:61], s[88:89], 0, v[64:65]
	s_waitcnt vmcnt(13)
	s_nop 1
	v_mov_b64_e32 v[56:57], v[176:177]
	v_mov_b64_e32 v[58:59], v[178:179]
	v_add_u32_e32 v214, 0xa0000, v213
	global_load_dwordx4 v[176:179], v214, s[88:89] offset:256
	s_nop 0
	s_waitcnt vmcnt(12)
	s_nop 1
	v_mov_b64_e32 v[60:61], v[180:181]
	v_mov_b64_e32 v[62:63], v[182:183]
	v_add_u32_e32 v214, 0x210000, v212
	global_load_dwordx4 v[180:183], v214, s[6:7]
	v_lshlrev_b32_e32 v66, 16, v56
	v_and_b32_e32 v67, 0xffff0000, v56
	v_lshlrev_b32_e32 v68, 16, v60
	v_and_b32_e32 v69, 0xffff0000, v60
	v_lshlrev_b32_e32 v56, 16, v57
	v_and_b32_e32 v57, 0xffff0000, v57
	v_lshlrev_b32_e32 v60, 16, v61
	v_and_b32_e32 v61, 0xffff0000, v61
	v_pk_fma_f32 v[54:55], v[54:55], v[56:57], v[60:61]
	v_lshlrev_b32_e32 v56, 16, v58
	v_and_b32_e32 v57, 0xffff0000, v58
	v_lshlrev_b32_e32 v60, 16, v62
	v_and_b32_e32 v61, 0xffff0000, v62
	v_pk_fma_f32 v[56:57], v[48:49], v[56:57], v[60:61]
	v_lshlrev_b32_e32 v48, 16, v59
	v_and_b32_e32 v49, 0xffff0000, v59
	v_lshlrev_b32_e32 v58, 16, v63
	v_and_b32_e32 v59, 0xffff0000, v63
	v_pk_fma_f32 v[52:53], v[52:53], v[66:67], v[68:69]
	v_pk_fma_f32 v[58:59], v[50:51], v[48:49], v[58:59]
	v_cvt_pk_bf16_f32 v48, v52, v53
	v_cvt_pk_bf16_f32 v49, v54, v55
	v_cvt_pk_bf16_f32 v50, v56, v57
	v_cvt_pk_bf16_f32 v51, v58, v59
	v_lshl_add_u64 v[52:53], s[8:9], 0, v[64:65]
	global_store_dwordx4 v[52:53], v[48:51], off
	s_nop 1
	v_add_u32_e32 v50, 0x90, v140
	v_ashrrev_i32_e32 v51, 31, v50
	v_lshlrev_b64 v[48:49], 11, v[50:51]
	v_lshl_add_u64 v[56:57], v[48:49], 0, v[138:139]
	v_mad_i64_i32 v[50:51], s[2:3], v50, s26, v[144:145]
	v_lshl_add_u64 v[50:51], v[50:51], 0, s[58:59]
	v_lshlrev_b64 v[60:61], 1, v[56:57]
	v_lshl_add_u64 v[52:53], v[50:51], 0, v[142:143]
	v_lshl_add_u64 v[56:57], s[88:89], 0, v[60:61]
	s_waitcnt vmcnt(13)
	s_nop 1
	v_mov_b64_e32 v[52:53], v[184:185]
	v_mov_b64_e32 v[54:55], v[186:187]
	v_add_u32_e32 v214, 0xb0000, v213
	global_load_dwordx4 v[184:187], v214, s[88:89]
	s_nop 0
	s_waitcnt vmcnt(12)
	s_nop 1
	v_mov_b64_e32 v[56:57], v[188:189]
	v_mov_b64_e32 v[58:59], v[190:191]
	v_add_u32_e32 v214, 0x210000, v212
	global_load_dwordx4 v[188:191], v214, s[6:7] offset:256
	v_lshlrev_b32_e32 v62, 16, v52
	v_and_b32_e32 v63, 0xffff0000, v52
	v_lshlrev_b32_e32 v64, 16, v56
	v_and_b32_e32 v65, 0xffff0000, v56
	v_lshlrev_b32_e32 v52, 16, v53
	v_and_b32_e32 v53, 0xffff0000, v53
	v_lshlrev_b32_e32 v56, 16, v57
	v_and_b32_e32 v57, 0xffff0000, v57
	v_pk_fma_f32 v[46:47], v[46:47], v[52:53], v[56:57]
	v_lshlrev_b32_e32 v52, 16, v54
	v_and_b32_e32 v53, 0xffff0000, v54
	v_lshlrev_b32_e32 v56, 16, v58
	v_and_b32_e32 v57, 0xffff0000, v58
	v_pk_fma_f32 v[52:53], v[40:41], v[52:53], v[56:57]
	v_lshlrev_b32_e32 v40, 16, v55
	v_and_b32_e32 v41, 0xffff0000, v55
	v_lshlrev_b32_e32 v54, 16, v59
	v_and_b32_e32 v55, 0xffff0000, v59
	v_pk_fma_f32 v[44:45], v[44:45], v[62:63], v[64:65]
	v_pk_fma_f32 v[54:55], v[42:43], v[40:41], v[54:55]
	v_cvt_pk_bf16_f32 v40, v44, v45
	v_cvt_pk_bf16_f32 v41, v46, v47
	v_cvt_pk_bf16_f32 v42, v52, v53
	v_cvt_pk_bf16_f32 v43, v54, v55
	v_lshl_add_u64 v[44:45], s[8:9], 0, v[60:61]
	global_store_dwordx4 v[44:45], v[40:43], off
	v_lshl_add_u64 v[44:45], v[48:49], 0, v[120:121]
	v_lshlrev_b64 v[48:49], 1, v[44:45]
	v_lshl_add_u64 v[40:41], v[50:51], 0, v[122:123]
	v_lshl_add_u64 v[44:45], s[88:89], 0, v[48:49]
	s_waitcnt vmcnt(13)
	s_nop 1
	v_mov_b64_e32 v[40:41], v[192:193]
	v_mov_b64_e32 v[42:43], v[194:195]
	v_add_u32_e32 v214, 0xb0000, v213
	global_load_dwordx4 v[192:195], v214, s[88:89] offset:256
	s_nop 0
	s_waitcnt vmcnt(12)
	s_nop 1
	v_mov_b64_e32 v[44:45], v[196:197]
	v_mov_b64_e32 v[46:47], v[198:199]
	v_lshlrev_b32_e32 v50, 16, v40
	v_and_b32_e32 v51, 0xffff0000, v40
	v_lshlrev_b32_e32 v52, 16, v44
	v_and_b32_e32 v53, 0xffff0000, v44
	v_lshlrev_b32_e32 v40, 16, v41
	v_and_b32_e32 v41, 0xffff0000, v41
	v_lshlrev_b32_e32 v44, 16, v45
	v_and_b32_e32 v45, 0xffff0000, v45
	v_pk_fma_f32 v[38:39], v[38:39], v[40:41], v[44:45]
	v_lshlrev_b32_e32 v40, 16, v42
	v_and_b32_e32 v41, 0xffff0000, v42
	v_lshlrev_b32_e32 v44, 16, v46
	v_and_b32_e32 v45, 0xffff0000, v46
	v_pk_fma_f32 v[40:41], v[32:33], v[40:41], v[44:45]
	v_lshlrev_b32_e32 v32, 16, v43
	v_and_b32_e32 v33, 0xffff0000, v43
	v_lshlrev_b32_e32 v42, 16, v47
	v_and_b32_e32 v43, 0xffff0000, v47
	v_pk_fma_f32 v[36:37], v[36:37], v[50:51], v[52:53]
	v_pk_fma_f32 v[42:43], v[34:35], v[32:33], v[42:43]
	v_cvt_pk_bf16_f32 v32, v36, v37
	v_cvt_pk_bf16_f32 v33, v38, v39
	v_cvt_pk_bf16_f32 v34, v40, v41
	v_cvt_pk_bf16_f32 v35, v42, v43
	v_lshl_add_u64 v[36:37], s[8:9], 0, v[48:49]
	global_store_dwordx4 v[36:37], v[32:35], off
	s_nop 1
	v_add_u32_e32 v34, 0xa0, v140
	v_ashrrev_i32_e32 v35, 31, v34
	v_lshlrev_b64 v[32:33], 11, v[34:35]
	v_lshl_add_u64 v[40:41], v[32:33], 0, v[138:139]
	v_mad_i64_i32 v[34:35], s[2:3], v34, s26, v[144:145]
	v_lshl_add_u64 v[34:35], v[34:35], 0, s[58:59]
	v_lshlrev_b64 v[44:45], 1, v[40:41]
	v_lshl_add_u64 v[36:37], v[34:35], 0, v[142:143]
	v_lshl_add_u64 v[40:41], s[88:89], 0, v[44:45]
	s_waitcnt vmcnt(12)
; __device__ __forceinline__ unsigned cvt_pk_bf16(float lo, float hi) { const f32x2_t v = {lo, hi}; const bf16x2_t b = __builtin_convertvector(v, bf16x2_t); return __builtin_bit_cast(unsigned, b); }
;     __device__ __forceinline__ void operator()(const Acc& acc, const Unit& u, int wr, int wc, int fr, int fq) const {
;     ...
; #pragma unroll
;         for (int ai = 0; ai < 2; ++ai)
; #pragma unroll
;             for (int m = 0; m < 4; ++m) {
;                 asm volatile("" ::: "memory");
;                 const int r = row0 + ai * HALF + m * 16;
; #pragma unroll
;                 for (int bj = 0; bj < 2; ++bj) {
;                     const int c = col0 + bj * HALF; const size_t off = (size_t)r * D + c;
;                     const u32x4 gw = *(const u32x4*)(gates + (size_t)r * 6144 + br * D + c);
;                     f32x4 v0, v1;
;                     v0[0] = acc[ai][bj][m][0][0] * bflo(gw.x); v0[1] = acc[ai][bj][m][0][1] * bfhi(gw.x); v0[2] = acc[ai][bj][m][0][2] * bflo(gw.y); v0[3] = acc[ai][bj][m][0][3] * bfhi(gw.y);
;                     v1[0] = acc[ai][bj][m][1][0] * bflo(gw.z); v1[1] = acc[ai][bj][m][1][1] * bfhi(gw.z); v1[2] = acc[ai][bj][m][1][2] * bflo(gw.w); v1[3] = acc[ai][bj][m][1][3] * bfhi(gw.w);
;                     if (br > 0) { const u32x4 ma = *(const u32x4*)(prev + off);
;                         v0[0] += bflo(ma.x); v0[1] += bfhi(ma.x); v0[2] += bflo(ma.y); v0[3] += bfhi(ma.y); v1[0] += bflo(ma.z); v1[1] += bfhi(ma.z); v1[2] += bflo(ma.w); v1[3] += bfhi(ma.w); }
;                     u32x4 w; w.x = cvt_pk_bf16(v0[0], v0[1]); w.y = cvt_pk_bf16(v0[2], v0[3]); w.z = cvt_pk_bf16(v1[0], v1[1]); w.w = cvt_pk_bf16(v1[2], v1[3]);
;                     *(u32x4*)(dst + off) = w;
;                 }
	s_nop 1
	v_mov_b64_e32 v[36:37], v[200:201]
	v_mov_b64_e32 v[38:39], v[202:203]
	s_nop 0
	s_waitcnt vmcnt(10)
	s_nop 1
	v_mov_b64_e32 v[40:41], v[204:205]
	v_mov_b64_e32 v[42:43], v[206:207]
	v_lshlrev_b32_e32 v46, 16, v36
	v_and_b32_e32 v47, 0xffff0000, v36
	v_lshlrev_b32_e32 v48, 16, v40
	v_and_b32_e32 v49, 0xffff0000, v40
	v_lshlrev_b32_e32 v36, 16, v37
	v_and_b32_e32 v37, 0xffff0000, v37
	v_lshlrev_b32_e32 v40, 16, v41
	v_and_b32_e32 v41, 0xffff0000, v41
	v_pk_fma_f32 v[30:31], v[30:31], v[36:37], v[40:41]
	v_lshlrev_b32_e32 v36, 16, v38
	v_and_b32_e32 v37, 0xffff0000, v38
	v_lshlrev_b32_e32 v40, 16, v42
	v_and_b32_e32 v41, 0xffff0000, v42
	v_pk_fma_f32 v[36:37], v[24:25], v[36:37], v[40:41]
	v_lshlrev_b32_e32 v24, 16, v39
	v_and_b32_e32 v25, 0xffff0000, v39
	v_lshlrev_b32_e32 v38, 16, v43
	v_and_b32_e32 v39, 0xffff0000, v43
	v_pk_fma_f32 v[28:29], v[28:29], v[46:47], v[48:49]
	v_pk_fma_f32 v[38:39], v[26:27], v[24:25], v[38:39]
	v_cvt_pk_bf16_f32 v24, v28, v29
	v_cvt_pk_bf16_f32 v25, v30, v31
	v_cvt_pk_bf16_f32 v26, v36, v37
	v_cvt_pk_bf16_f32 v27, v38, v39
	v_lshl_add_u64 v[28:29], s[8:9], 0, v[44:45]
	global_store_dwordx4 v[28:29], v[24:27], off
	v_lshl_add_u64 v[28:29], v[32:33], 0, v[120:121]
	v_lshlrev_b64 v[32:33], 1, v[28:29]
	v_lshl_add_u64 v[24:25], v[34:35], 0, v[122:123]
	v_lshl_add_u64 v[28:29], s[88:89], 0, v[32:33]
	s_waitcnt vmcnt(10)
	s_nop 1
	v_mov_b64_e32 v[24:25], v[208:209]
	v_mov_b64_e32 v[26:27], v[210:211]
	s_nop 0
	s_waitcnt vmcnt(8)
	s_nop 1
	v_mov_b64_e32 v[28:29], v[176:177]
	v_mov_b64_e32 v[30:31], v[178:179]
	v_lshlrev_b32_e32 v34, 16, v24
	v_and_b32_e32 v35, 0xffff0000, v24
	v_lshlrev_b32_e32 v36, 16, v28
	v_and_b32_e32 v37, 0xffff0000, v28
	v_lshlrev_b32_e32 v24, 16, v25
	v_and_b32_e32 v25, 0xffff0000, v25
	v_lshlrev_b32_e32 v28, 16, v29
	v_and_b32_e32 v29, 0xffff0000, v29
	v_pk_fma_f32 v[22:23], v[22:23], v[24:25], v[28:29]
	v_lshlrev_b32_e32 v24, 16, v26
	v_and_b32_e32 v25, 0xffff0000, v26
	v_lshlrev_b32_e32 v28, 16, v30
	v_and_b32_e32 v29, 0xffff0000, v30
	v_pk_fma_f32 v[24:25], v[16:17], v[24:25], v[28:29]
	v_lshlrev_b32_e32 v16, 16, v27
	v_and_b32_e32 v17, 0xffff0000, v27
	v_lshlrev_b32_e32 v26, 16, v31
	v_and_b32_e32 v27, 0xffff0000, v31
	v_pk_fma_f32 v[20:21], v[20:21], v[34:35], v[36:37]
	v_pk_fma_f32 v[26:27], v[18:19], v[16:17], v[26:27]
	v_cvt_pk_bf16_f32 v16, v20, v21
	v_cvt_pk_bf16_f32 v17, v22, v23
	v_cvt_pk_bf16_f32 v18, v24, v25
	v_cvt_pk_bf16_f32 v19, v26, v27
	v_lshl_add_u64 v[20:21], s[8:9], 0, v[32:33]
	global_store_dwordx4 v[20:21], v[16:19], off
	s_nop 1
	v_add_u32_e32 v18, 0xb0, v140
	v_ashrrev_i32_e32 v19, 31, v18
	v_lshlrev_b64 v[16:17], 11, v[18:19]
	v_lshl_add_u64 v[24:25], v[16:17], 0, v[138:139]
	v_mad_i64_i32 v[18:19], s[2:3], v18, s26, v[144:145]
	v_lshl_add_u64 v[18:19], v[18:19], 0, s[58:59]
	v_lshlrev_b64 v[28:29], 1, v[24:25]
	v_lshl_add_u64 v[20:21], v[18:19], 0, v[142:143]
	v_lshl_add_u64 v[24:25], s[88:89], 0, v[28:29]
	s_waitcnt vmcnt(8)
	s_nop 1
	v_mov_b64_e32 v[20:21], v[180:181]
	v_mov_b64_e32 v[22:23], v[182:183]
	s_nop 0
	s_waitcnt vmcnt(6)
	s_nop 1
	v_mov_b64_e32 v[24:25], v[184:185]
	v_mov_b64_e32 v[26:27], v[186:187]
	v_lshlrev_b32_e32 v30, 16, v20
	v_and_b32_e32 v31, 0xffff0000, v20
	v_lshlrev_b32_e32 v32, 16, v24
	v_and_b32_e32 v33, 0xffff0000, v24
	v_lshlrev_b32_e32 v20, 16, v21
	v_and_b32_e32 v21, 0xffff0000, v21
	v_lshlrev_b32_e32 v24, 16, v25
	v_and_b32_e32 v25, 0xffff0000, v25
	v_pk_fma_f32 v[14:15], v[14:15], v[20:21], v[24:25]
	v_lshlrev_b32_e32 v20, 16, v22
	v_and_b32_e32 v21, 0xffff0000, v22
	v_lshlrev_b32_e32 v24, 16, v26
	v_and_b32_e32 v25, 0xffff0000, v26
	v_pk_fma_f32 v[20:21], v[8:9], v[20:21], v[24:25]
	v_lshlrev_b32_e32 v8, 16, v23
	v_and_b32_e32 v9, 0xffff0000, v23
	v_lshlrev_b32_e32 v22, 16, v27
	v_and_b32_e32 v23, 0xffff0000, v27
	v_pk_fma_f32 v[12:13], v[12:13], v[30:31], v[32:33]
	v_pk_fma_f32 v[22:23], v[10:11], v[8:9], v[22:23]
	v_cvt_pk_bf16_f32 v8, v12, v13
	v_cvt_pk_bf16_f32 v9, v14, v15
	v_cvt_pk_bf16_f32 v10, v20, v21
	v_cvt_pk_bf16_f32 v11, v22, v23
	v_lshl_add_u64 v[12:13], s[8:9], 0, v[28:29]
	global_store_dwordx4 v[12:13], v[8:11], off
	v_lshl_add_u64 v[12:13], v[16:17], 0, v[120:121]
	v_lshlrev_b64 v[16:17], 1, v[12:13]
	v_lshl_add_u64 v[8:9], v[18:19], 0, v[122:123]
	v_lshl_add_u64 v[12:13], s[88:89], 0, v[16:17]
	s_waitcnt vmcnt(6)
	s_nop 1
	v_mov_b64_e32 v[8:9], v[188:189]
	v_mov_b64_e32 v[10:11], v[190:191]
	s_nop 0
	s_waitcnt vmcnt(4)
	s_nop 1
	v_mov_b64_e32 v[12:13], v[192:193]
	v_mov_b64_e32 v[14:15], v[194:195]
	v_lshlrev_b32_e32 v18, 16, v8
	v_and_b32_e32 v19, 0xffff0000, v8
	v_lshlrev_b32_e32 v20, 16, v12
	v_and_b32_e32 v21, 0xffff0000, v12
	v_lshlrev_b32_e32 v8, 16, v9
	v_and_b32_e32 v9, 0xffff0000, v9
	v_lshlrev_b32_e32 v12, 16, v13
	v_and_b32_e32 v13, 0xffff0000, v13
	v_pk_fma_f32 v[6:7], v[6:7], v[8:9], v[12:13]
	v_lshlrev_b32_e32 v8, 16, v10
	v_and_b32_e32 v9, 0xffff0000, v10
	v_lshlrev_b32_e32 v12, 16, v14
	v_and_b32_e32 v13, 0xffff0000, v14
	v_pk_fma_f32 v[8:9], v[0:1], v[8:9], v[12:13]
	v_lshlrev_b32_e32 v0, 16, v11
	v_and_b32_e32 v1, 0xffff0000, v11
	v_lshlrev_b32_e32 v10, 16, v15
	v_and_b32_e32 v11, 0xffff0000, v15
	v_pk_fma_f32 v[4:5], v[4:5], v[18:19], v[20:21]
	v_pk_fma_f32 v[10:11], v[2:3], v[0:1], v[10:11]
	v_cvt_pk_bf16_f32 v0, v4, v5
	v_cvt_pk_bf16_f32 v1, v6, v7
	v_cvt_pk_bf16_f32 v2, v8, v9
	v_cvt_pk_bf16_f32 v3, v10, v11
	v_lshl_add_u64 v[4:5], s[8:9], 0, v[16:17]
	global_store_dwordx4 v[4:5], v[0:3], off
	s_cbranch_vccnz .LBB0_203
	s_andn2_b64 vcc, exec, s[10:11]
	s_cbranch_vccnz .LBB0_202
	s_barrier
	s_branch .LBB0_202

; __device__ __forceinline__ unsigned cvt_pk_bf16(float lo, float hi) { const f32x2_t v = {lo, hi}; const bf16x2_t b = __builtin_convertvector(v, bf16x2_t); return __builtin_bit_cast(unsigned, b); }
;     __device__ __forceinline__ void operator()(const Acc& acc, const Unit& u, int wr, int wc, int fr, int fq) const {
;     ...
; #pragma unroll
;         for (int ai = 0; ai < 2; ++ai)
; #pragma unroll
;             for (int m = 0; m < 4; ++m) {
;                 asm volatile("" ::: "memory");
;                 const int r = row0 + ai * HALF + m * 16;
; #pragma unroll
;                 for (int bj = 0; bj < 2; ++bj) {
;                     const int c = col0 + bj * HALF; const size_t off = (size_t)r * D + c;
;                     const u32x4 gw = *(const u32x4*)(gates + (size_t)r * 6144 + br * D + c);
;                     f32x4 v0, v1;
;                     v0[0] = acc[ai][bj][m][0][0] * bflo(gw.x); v0[1] = acc[ai][bj][m][0][1] * bfhi(gw.x); v0[2] = acc[ai][bj][m][0][2] * bflo(gw.y); v0[3] = acc[ai][bj][m][0][3] * bfhi(gw.y);
;                     v1[0] = acc[ai][bj][m][1][0] * bflo(gw.z); v1[1] = acc[ai][bj][m][1][1] * bfhi(gw.z); v1[2] = acc[ai][bj][m][1][2] * bflo(gw.w); v1[3] = acc[ai][bj][m][1][3] * bfhi(gw.w);
;                     if (br > 0) { const u32x4 ma = *(const u32x4*)(prev + off);
;                         v0[0] += bflo(ma.x); v0[1] += bfhi(ma.x); v0[2] += bflo(ma.y); v0[3] += bfhi(ma.y); v1[0] += bflo(ma.z); v1[1] += bfhi(ma.z); v1[2] += bflo(ma.w); v1[3] += bfhi(ma.w); }
;                     u32x4 w; w.x = cvt_pk_bf16(v0[0], v0[1]); w.y = cvt_pk_bf16(v0[2], v0[3]); w.z = cvt_pk_bf16(v1[0], v1[1]); w.w = cvt_pk_bf16(v1[2], v1[3]);
;                     *(u32x4*)(dst + off) = w;
;                 }
.LBB0_240:
	v_lshl_or_b32 v138, s83, 8, v146
	v_lshl_add_u32 v140, s82, 8, v144
	v_ashrrev_i32_e32 v139, 31, v138
	v_mov_b64_e32 v[142:143], s[10:11]
	v_mad_i64_i32 v[148:149], s[2:3], v140, s26, v[142:143]
	v_lshlrev_b64 v[138:139], 1, v[138:139]
	v_lshl_add_u64 v[152:153], v[148:149], 0, v[138:139]
	v_subrev_u32_e32 v214, s10, v152
	global_load_dwordx4 v[170:173], v214, s[10:11]
	global_load_dwordx4 v[174:177], v214, s[10:11] offset:256
	v_add_u32_e32 v215, 0x30000, v214
	global_load_dwordx4 v[178:181], v215, s[10:11]
	v_add_u32_e32 v215, 0x30000, v214
	global_load_dwordx4 v[182:185], v215, s[10:11] offset:256
	v_add_u32_e32 v215, 0x60000, v214
	global_load_dwordx4 v[186:189], v215, s[10:11]
	v_add_u32_e32 v215, 0x60000, v214
	global_load_dwordx4 v[190:193], v215, s[10:11] offset:256
	v_add_u32_e32 v215, 0x90000, v214
	global_load_dwordx4 v[194:197], v215, s[10:11]
	v_add_u32_e32 v215, 0x90000, v214
	global_load_dwordx4 v[198:201], v215, s[10:11] offset:256
	v_add_u32_e32 v215, 0x180000, v214
	global_load_dwordx4 v[202:205], v215, s[10:11]
	v_add_u32_e32 v215, 0x180000, v214
	global_load_dwordx4 v[206:209], v215, s[10:11] offset:256
	v_add_u32_e32 v215, 0x1b0000, v214
	global_load_dwordx4 v[210:213], v215, s[10:11]
	s_waitcnt vmcnt(10)
	s_nop 1
	v_mov_b64_e32 v[148:149], v[170:171]
	v_mov_b64_e32 v[150:151], v[172:173]
	v_add_u32_e32 v215, 0x1b0000, v214
	global_load_dwordx4 v[170:173], v215, s[10:11] offset:256
	v_ashrrev_i32_e32 v141, 31, v140
	s_mov_b64 s[24:25], -1
	s_andn2_b64 vcc, exec, s[4:5]
	v_lshlrev_b32_e32 v154, 16, v148
	v_and_b32_e32 v155, 0xffff0000, v148
	v_lshlrev_b32_e32 v148, 16, v149
	v_and_b32_e32 v149, 0xffff0000, v149
	v_pk_mul_f32 v[126:127], v[126:127], v[148:149]
	v_lshlrev_b32_e32 v148, 16, v150
	v_and_b32_e32 v149, 0xffff0000, v150
	v_pk_mul_f32 v[124:125], v[124:125], v[154:155]
	v_pk_mul_f32 v[148:149], v[120:121], v[148:149]
	v_lshlrev_b32_e32 v120, 16, v151
	v_and_b32_e32 v121, 0xffff0000, v151
	v_pk_mul_f32 v[150:151], v[122:123], v[120:121]
	v_cvt_pk_bf16_f32 v120, v124, v125
	v_lshlrev_b64 v[124:125], 12, v[140:141]
	v_lshl_add_u64 v[124:125], s[12:13], 0, v[124:125]
	v_cvt_pk_bf16_f32 v121, v126, v127
	v_cvt_pk_bf16_f32 v122, v148, v149
	v_cvt_pk_bf16_f32 v123, v150, v151
	v_lshl_add_u64 v[124:125], v[124:125], 0, v[138:139]
	global_store_dwordx4 v[124:125], v[120:123], off
	s_waitcnt vmcnt(11)
	s_nop 1
	v_mov_b64_e32 v[120:121], v[174:175]
	v_mov_b64_e32 v[122:123], v[176:177]
	v_add_u32_e32 v215, 0x1e0000, v214
	global_load_dwordx4 v[174:177], v215, s[10:11]
	v_lshlrev_b32_e32 v126, 16, v120
	v_and_b32_e32 v127, 0xffff0000, v120
	v_lshlrev_b32_e32 v120, 16, v121
	v_and_b32_e32 v121, 0xffff0000, v121
	v_pk_mul_f32 v[118:119], v[118:119], v[120:121]
	v_lshlrev_b32_e32 v120, 16, v122
	v_and_b32_e32 v121, 0xffff0000, v122
	v_pk_mul_f32 v[120:121], v[112:113], v[120:121]
	v_lshlrev_b32_e32 v112, 16, v123
	v_and_b32_e32 v113, 0xffff0000, v123
	v_pk_mul_f32 v[116:117], v[116:117], v[126:127]
	v_pk_mul_f32 v[122:123], v[114:115], v[112:113]
	v_cvt_pk_bf16_f32 v112, v116, v117
	v_cvt_pk_bf16_f32 v113, v118, v119
	v_cvt_pk_bf16_f32 v114, v120, v121
	v_cvt_pk_bf16_f32 v115, v122, v123
	v_or_b32_e32 v118, 16, v140
	global_store_dwordx4 v[124:125], v[112:115], off offset:256
	v_ashrrev_i32_e32 v119, 31, v118
	s_nop 0
	v_mad_i64_i32 v[112:113], s[2:3], v118, s26, v[142:143]
	v_lshl_add_u64 v[112:113], v[112:113], 0, v[138:139]
	s_waitcnt vmcnt(12)
	s_nop 1
	v_mov_b64_e32 v[114:115], v[178:179]
	v_mov_b64_e32 v[116:117], v[180:181]
	v_add_u32_e32 v215, 0x1e0000, v214
	global_load_dwordx4 v[178:181], v215, s[10:11] offset:256
	v_lshlrev_b32_e32 v120, 16, v114
	v_and_b32_e32 v121, 0xffff0000, v114
	v_lshlrev_b32_e32 v114, 16, v115
	v_and_b32_e32 v115, 0xffff0000, v115
	v_pk_mul_f32 v[110:111], v[110:111], v[114:115]
	v_lshlrev_b32_e32 v114, 16, v116
	v_and_b32_e32 v115, 0xffff0000, v116
	v_pk_mul_f32 v[108:109], v[108:109], v[120:121]
	v_pk_mul_f32 v[114:115], v[104:105], v[114:115]
	v_lshlrev_b32_e32 v104, 16, v117
	v_and_b32_e32 v105, 0xffff0000, v117
	v_pk_mul_f32 v[116:117], v[106:107], v[104:105]
	v_cvt_pk_bf16_f32 v104, v108, v109
	v_lshlrev_b64 v[108:109], 12, v[118:119]
	v_lshl_add_u64 v[108:109], s[12:13], 0, v[108:109]
	v_cvt_pk_bf16_f32 v105, v110, v111
	v_cvt_pk_bf16_f32 v106, v114, v115
	v_cvt_pk_bf16_f32 v107, v116, v117
	v_lshl_add_u64 v[108:109], v[108:109], 0, v[138:139]
	global_store_dwordx4 v[108:109], v[104:107], off
	s_waitcnt vmcnt(13)
	s_nop 1
	v_mov_b64_e32 v[104:105], v[182:183]
	v_mov_b64_e32 v[106:107], v[184:185]
	v_add_u32_e32 v215, 0x210000, v214
	global_load_dwordx4 v[182:185], v215, s[10:11]
	v_lshlrev_b32_e32 v110, 16, v104
	v_and_b32_e32 v111, 0xffff0000, v104
	v_lshlrev_b32_e32 v104, 16, v105
	v_and_b32_e32 v105, 0xffff0000, v105
	v_pk_mul_f32 v[102:103], v[102:103], v[104:105]
	v_lshlrev_b32_e32 v104, 16, v106
	v_and_b32_e32 v105, 0xffff0000, v106
	v_pk_mul_f32 v[104:105], v[96:97], v[104:105]
	v_lshlrev_b32_e32 v96, 16, v107
	v_and_b32_e32 v97, 0xffff0000, v107
	v_pk_mul_f32 v[100:101], v[100:101], v[110:111]
	v_pk_mul_f32 v[106:107], v[98:99], v[96:97]
	v_cvt_pk_bf16_f32 v96, v100, v101
	v_cvt_pk_bf16_f32 v97, v102, v103
	v_cvt_pk_bf16_f32 v98, v104, v105
	v_cvt_pk_bf16_f32 v99, v106, v107
	v_or_b32_e32 v102, 32, v140
	global_store_dwordx4 v[108:109], v[96:99], off offset:256
	v_ashrrev_i32_e32 v103, 31, v102
	s_nop 0
	v_mad_i64_i32 v[96:97], s[2:3], v102, s26, v[142:143]
	v_lshl_add_u64 v[96:97], v[96:97], 0, v[138:139]
	s_waitcnt vmcnt(14)
; __device__ __forceinline__ unsigned cvt_pk_bf16(float lo, float hi) { const f32x2_t v = {lo, hi}; const bf16x2_t b = __builtin_convertvector(v, bf16x2_t); return __builtin_bit_cast(unsigned, b); }
;     __device__ __forceinline__ void operator()(const Acc& acc, const Unit& u, int wr, int wc, int fr, int fq) const {
;     ...
; #pragma unroll
;         for (int ai = 0; ai < 2; ++ai)
; #pragma unroll
;             for (int m = 0; m < 4; ++m) {
;                 asm volatile("" ::: "memory");
;                 const int r = row0 + ai * HALF + m * 16;
; #pragma unroll
;                 for (int bj = 0; bj < 2; ++bj) {
;                     const int c = col0 + bj * HALF; const size_t off = (size_t)r * D + c;
;                     const u32x4 gw = *(const u32x4*)(gates + (size_t)r * 6144 + br * D + c);
;                     f32x4 v0, v1;
;                     v0[0] = acc[ai][bj][m][0][0] * bflo(gw.x); v0[1] = acc[ai][bj][m][0][1] * bfhi(gw.x); v0[2] = acc[ai][bj][m][0][2] * bflo(gw.y); v0[3] = acc[ai][bj][m][0][3] * bfhi(gw.y);
;                     v1[0] = acc[ai][bj][m][1][0] * bflo(gw.z); v1[1] = acc[ai][bj][m][1][1] * bfhi(gw.z); v1[2] = acc[ai][bj][m][1][2] * bflo(gw.w); v1[3] = acc[ai][bj][m][1][3] * bfhi(gw.w);
;                     if (br > 0) { const u32x4 ma = *(const u32x4*)(prev + off);
;                         v0[0] += bflo(ma.x); v0[1] += bfhi(ma.x); v0[2] += bflo(ma.y); v0[3] += bfhi(ma.y); v1[0] += bflo(ma.z); v1[1] += bfhi(ma.z); v1[2] += bflo(ma.w); v1[3] += bfhi(ma.w); }
;                     u32x4 w; w.x = cvt_pk_bf16(v0[0], v0[1]); w.y = cvt_pk_bf16(v0[2], v0[3]); w.z = cvt_pk_bf16(v1[0], v1[1]); w.w = cvt_pk_bf16(v1[2], v1[3]);
;                     *(u32x4*)(dst + off) = w;
;                 }
	s_nop 1
	v_mov_b64_e32 v[98:99], v[186:187]
	v_mov_b64_e32 v[100:101], v[188:189]
	v_add_u32_e32 v215, 0x210000, v214
	global_load_dwordx4 v[186:189], v215, s[10:11] offset:256
	v_lshlrev_b32_e32 v104, 16, v98
	v_and_b32_e32 v105, 0xffff0000, v98
	v_lshlrev_b32_e32 v98, 16, v99
	v_and_b32_e32 v99, 0xffff0000, v99
	v_pk_mul_f32 v[94:95], v[94:95], v[98:99]
	v_lshlrev_b32_e32 v98, 16, v100
	v_and_b32_e32 v99, 0xffff0000, v100
	v_pk_mul_f32 v[92:93], v[92:93], v[104:105]
	v_pk_mul_f32 v[98:99], v[88:89], v[98:99]
	v_lshlrev_b32_e32 v88, 16, v101
	v_and_b32_e32 v89, 0xffff0000, v101
	v_pk_mul_f32 v[100:101], v[90:91], v[88:89]
	v_cvt_pk_bf16_f32 v88, v92, v93
	v_lshlrev_b64 v[92:93], 12, v[102:103]
	v_lshl_add_u64 v[92:93], s[12:13], 0, v[92:93]
	v_cvt_pk_bf16_f32 v89, v94, v95
	v_cvt_pk_bf16_f32 v90, v98, v99
	v_cvt_pk_bf16_f32 v91, v100, v101
	v_lshl_add_u64 v[92:93], v[92:93], 0, v[138:139]
	global_store_dwordx4 v[92:93], v[88:91], off
	s_waitcnt vmcnt(15)
	s_nop 1
	v_mov_b64_e32 v[88:89], v[190:191]
	v_mov_b64_e32 v[90:91], v[192:193]
	v_lshlrev_b32_e32 v94, 16, v88
	v_and_b32_e32 v95, 0xffff0000, v88
	v_lshlrev_b32_e32 v88, 16, v89
	v_and_b32_e32 v89, 0xffff0000, v89
	v_pk_mul_f32 v[86:87], v[86:87], v[88:89]
	v_lshlrev_b32_e32 v88, 16, v90
	v_and_b32_e32 v89, 0xffff0000, v90
	v_pk_mul_f32 v[88:89], v[80:81], v[88:89]
	v_lshlrev_b32_e32 v80, 16, v91
	v_and_b32_e32 v81, 0xffff0000, v91
	v_pk_mul_f32 v[84:85], v[84:85], v[94:95]
	v_pk_mul_f32 v[90:91], v[82:83], v[80:81]
	v_cvt_pk_bf16_f32 v80, v84, v85
	v_cvt_pk_bf16_f32 v81, v86, v87
	v_cvt_pk_bf16_f32 v82, v88, v89
	v_cvt_pk_bf16_f32 v83, v90, v91
	v_or_b32_e32 v86, 48, v140
	global_store_dwordx4 v[92:93], v[80:83], off offset:256
	v_ashrrev_i32_e32 v87, 31, v86
	s_nop 0
	v_mad_i64_i32 v[80:81], s[2:3], v86, s26, v[142:143]
	v_lshl_add_u64 v[80:81], v[80:81], 0, v[138:139]
	s_waitcnt vmcnt(15)
	s_nop 1
	v_mov_b64_e32 v[82:83], v[194:195]
	v_mov_b64_e32 v[84:85], v[196:197]
	v_lshlrev_b32_e32 v88, 16, v82
	v_and_b32_e32 v89, 0xffff0000, v82
	v_lshlrev_b32_e32 v82, 16, v83
	v_and_b32_e32 v83, 0xffff0000, v83
	v_pk_mul_f32 v[78:79], v[78:79], v[82:83]
	v_lshlrev_b32_e32 v82, 16, v84
	v_and_b32_e32 v83, 0xffff0000, v84
	v_pk_mul_f32 v[76:77], v[76:77], v[88:89]
	v_pk_mul_f32 v[82:83], v[72:73], v[82:83]
	v_lshlrev_b32_e32 v72, 16, v85
	v_and_b32_e32 v73, 0xffff0000, v85
	v_pk_mul_f32 v[84:85], v[74:75], v[72:73]
	v_cvt_pk_bf16_f32 v72, v76, v77
	v_lshlrev_b64 v[76:77], 12, v[86:87]
	v_lshl_add_u64 v[76:77], s[12:13], 0, v[76:77]
	v_cvt_pk_bf16_f32 v73, v78, v79
	v_cvt_pk_bf16_f32 v74, v82, v83
	v_cvt_pk_bf16_f32 v75, v84, v85
	v_lshl_add_u64 v[76:77], v[76:77], 0, v[138:139]
	global_store_dwordx4 v[76:77], v[72:75], off
	s_waitcnt vmcnt(15)
	s_nop 1
	v_mov_b64_e32 v[72:73], v[198:199]
	v_mov_b64_e32 v[74:75], v[200:201]
	v_lshlrev_b32_e32 v78, 16, v72
	v_and_b32_e32 v79, 0xffff0000, v72
	v_lshlrev_b32_e32 v72, 16, v73
	v_and_b32_e32 v73, 0xffff0000, v73
	v_pk_mul_f32 v[70:71], v[70:71], v[72:73]
	v_lshlrev_b32_e32 v72, 16, v74
	v_and_b32_e32 v73, 0xffff0000, v74
	v_pk_mul_f32 v[72:73], v[64:65], v[72:73]
	v_lshlrev_b32_e32 v64, 16, v75
	v_and_b32_e32 v65, 0xffff0000, v75
	v_pk_mul_f32 v[68:69], v[68:69], v[78:79]
	v_pk_mul_f32 v[74:75], v[66:67], v[64:65]
	v_cvt_pk_bf16_f32 v64, v68, v69
	v_cvt_pk_bf16_f32 v65, v70, v71
	v_cvt_pk_bf16_f32 v66, v72, v73
	v_cvt_pk_bf16_f32 v67, v74, v75
	v_add_u32_e32 v70, 0x80, v140
	global_store_dwordx4 v[76:77], v[64:67], off offset:256
	v_ashrrev_i32_e32 v71, 31, v70
	s_nop 0
	v_mad_i64_i32 v[64:65], s[2:3], v70, s26, v[142:143]
	v_lshl_add_u64 v[64:65], v[64:65], 0, v[138:139]
	s_waitcnt vmcnt(15)
	s_nop 1
	v_mov_b64_e32 v[66:67], v[202:203]
	v_mov_b64_e32 v[68:69], v[204:205]
	v_lshlrev_b32_e32 v72, 16, v66
	v_and_b32_e32 v73, 0xffff0000, v66
	v_lshlrev_b32_e32 v66, 16, v67
	v_and_b32_e32 v67, 0xffff0000, v67
	v_pk_mul_f32 v[62:63], v[62:63], v[66:67]
	v_lshlrev_b32_e32 v66, 16, v68
	v_and_b32_e32 v67, 0xffff0000, v68
	v_pk_mul_f32 v[60:61], v[60:61], v[72:73]
	v_pk_mul_f32 v[66:67], v[56:57], v[66:67]
	v_lshlrev_b32_e32 v56, 16, v69
	v_and_b32_e32 v57, 0xffff0000, v69
	v_pk_mul_f32 v[68:69], v[58:59], v[56:57]
	v_cvt_pk_bf16_f32 v56, v60, v61
	v_lshlrev_b64 v[60:61], 12, v[70:71]
	v_lshl_add_u64 v[60:61], s[12:13], 0, v[60:61]
	v_cvt_pk_bf16_f32 v57, v62, v63
	v_cvt_pk_bf16_f32 v58, v66, v67
	v_cvt_pk_bf16_f32 v59, v68, v69
	v_lshl_add_u64 v[60:61], v[60:61], 0, v[138:139]
	global_store_dwordx4 v[60:61], v[56:59], off
	s_waitcnt vmcnt(15)
	s_nop 1
	v_mov_b64_e32 v[56:57], v[206:207]
	v_mov_b64_e32 v[58:59], v[208:209]
	v_lshlrev_b32_e32 v62, 16, v56
	v_and_b32_e32 v63, 0xffff0000, v56
	v_lshlrev_b32_e32 v56, 16, v57
	v_and_b32_e32 v57, 0xffff0000, v57
	v_pk_mul_f32 v[54:55], v[54:55], v[56:57]
	v_lshlrev_b32_e32 v56, 16, v58
	v_and_b32_e32 v57, 0xffff0000, v58
	v_pk_mul_f32 v[56:57], v[48:49], v[56:57]
	v_lshlrev_b32_e32 v48, 16, v59
	v_and_b32_e32 v49, 0xffff0000, v59
	v_pk_mul_f32 v[52:53], v[52:53], v[62:63]
	v_pk_mul_f32 v[58:59], v[50:51], v[48:49]
	v_cvt_pk_bf16_f32 v48, v52, v53
	v_cvt_pk_bf16_f32 v49, v54, v55
	v_cvt_pk_bf16_f32 v50, v56, v57
	v_cvt_pk_bf16_f32 v51, v58, v59
	v_add_u32_e32 v54, 0x90, v140
	global_store_dwordx4 v[60:61], v[48:51], off offset:256
	v_ashrrev_i32_e32 v55, 31, v54
	s_nop 0
	v_mad_i64_i32 v[48:49], s[2:3], v54, s26, v[142:143]
	v_lshl_add_u64 v[48:49], v[48:49], 0, v[138:139]
	s_waitcnt vmcnt(15)
; __device__ __forceinline__ unsigned cvt_pk_bf16(float lo, float hi) { const f32x2_t v = {lo, hi}; const bf16x2_t b = __builtin_convertvector(v, bf16x2_t); return __builtin_bit_cast(unsigned, b); }
;     __device__ __forceinline__ void operator()(const Acc& acc, const Unit& u, int wr, int wc, int fr, int fq) const {
;     ...
; #pragma unroll
;         for (int ai = 0; ai < 2; ++ai)
; #pragma unroll
;             for (int m = 0; m < 4; ++m) {
;                 asm volatile("" ::: "memory");
;                 const int r = row0 + ai * HALF + m * 16;
; #pragma unroll
;                 for (int bj = 0; bj < 2; ++bj) {
;                     const int c = col0 + bj * HALF; const size_t off = (size_t)r * D + c;
;                     const u32x4 gw = *(const u32x4*)(gates + (size_t)r * 6144 + br * D + c);
;                     f32x4 v0, v1;
;                     v0[0] = acc[ai][bj][m][0][0] * bflo(gw.x); v0[1] = acc[ai][bj][m][0][1] * bfhi(gw.x); v0[2] = acc[ai][bj][m][0][2] * bflo(gw.y); v0[3] = acc[ai][bj][m][0][3] * bfhi(gw.y);
;                     v1[0] = acc[ai][bj][m][1][0] * bflo(gw.z); v1[1] = acc[ai][bj][m][1][1] * bfhi(gw.z); v1[2] = acc[ai][bj][m][1][2] * bflo(gw.w); v1[3] = acc[ai][bj][m][1][3] * bfhi(gw.w);
;                     if (br > 0) { const u32x4 ma = *(const u32x4*)(prev + off);
;                         v0[0] += bflo(ma.x); v0[1] += bfhi(ma.x); v0[2] += bflo(ma.y); v0[3] += bfhi(ma.y); v1[0] += bflo(ma.z); v1[1] += bfhi(ma.z); v1[2] += bflo(ma.w); v1[3] += bfhi(ma.w); }
;                     u32x4 w; w.x = cvt_pk_bf16(v0[0], v0[1]); w.y = cvt_pk_bf16(v0[2], v0[3]); w.z = cvt_pk_bf16(v1[0], v1[1]); w.w = cvt_pk_bf16(v1[2], v1[3]);
;                     *(u32x4*)(dst + off) = w;
;                 }
	s_nop 1
	v_mov_b64_e32 v[50:51], v[210:211]
	v_mov_b64_e32 v[52:53], v[212:213]
	v_lshlrev_b32_e32 v56, 16, v50
	v_and_b32_e32 v57, 0xffff0000, v50
	v_lshlrev_b32_e32 v50, 16, v51
	v_and_b32_e32 v51, 0xffff0000, v51
	v_pk_mul_f32 v[46:47], v[46:47], v[50:51]
	v_lshlrev_b32_e32 v50, 16, v52
	v_and_b32_e32 v51, 0xffff0000, v52
	v_pk_mul_f32 v[44:45], v[44:45], v[56:57]
	v_pk_mul_f32 v[50:51], v[40:41], v[50:51]
	v_lshlrev_b32_e32 v40, 16, v53
	v_and_b32_e32 v41, 0xffff0000, v53
	v_pk_mul_f32 v[52:53], v[42:43], v[40:41]
	v_cvt_pk_bf16_f32 v40, v44, v45
	v_lshlrev_b64 v[44:45], 12, v[54:55]
	v_lshl_add_u64 v[44:45], s[12:13], 0, v[44:45]
	v_cvt_pk_bf16_f32 v41, v46, v47
	v_cvt_pk_bf16_f32 v42, v50, v51
	v_cvt_pk_bf16_f32 v43, v52, v53
	v_lshl_add_u64 v[44:45], v[44:45], 0, v[138:139]
	global_store_dwordx4 v[44:45], v[40:43], off
	s_waitcnt vmcnt(15)
	s_nop 1
	v_mov_b64_e32 v[40:41], v[170:171]
	v_mov_b64_e32 v[42:43], v[172:173]
	v_lshlrev_b32_e32 v46, 16, v40
	v_and_b32_e32 v47, 0xffff0000, v40
	v_lshlrev_b32_e32 v40, 16, v41
	v_and_b32_e32 v41, 0xffff0000, v41
	v_pk_mul_f32 v[38:39], v[38:39], v[40:41]
	v_lshlrev_b32_e32 v40, 16, v42
	v_and_b32_e32 v41, 0xffff0000, v42
	v_pk_mul_f32 v[40:41], v[32:33], v[40:41]
	v_lshlrev_b32_e32 v32, 16, v43
	v_and_b32_e32 v33, 0xffff0000, v43
	v_pk_mul_f32 v[36:37], v[36:37], v[46:47]
	v_pk_mul_f32 v[42:43], v[34:35], v[32:33]
	v_cvt_pk_bf16_f32 v32, v36, v37
	v_cvt_pk_bf16_f32 v33, v38, v39
	v_cvt_pk_bf16_f32 v34, v40, v41
	v_cvt_pk_bf16_f32 v35, v42, v43
	v_add_u32_e32 v38, 0xa0, v140
	global_store_dwordx4 v[44:45], v[32:35], off offset:256
	v_ashrrev_i32_e32 v39, 31, v38
	s_nop 0
	v_mad_i64_i32 v[32:33], s[2:3], v38, s26, v[142:143]
	v_lshl_add_u64 v[32:33], v[32:33], 0, v[138:139]
	s_waitcnt vmcnt(14)
	s_nop 1
	v_mov_b64_e32 v[34:35], v[174:175]
	v_mov_b64_e32 v[36:37], v[176:177]
	v_lshlrev_b32_e32 v40, 16, v34
	v_and_b32_e32 v41, 0xffff0000, v34
	v_lshlrev_b32_e32 v34, 16, v35
	v_and_b32_e32 v35, 0xffff0000, v35
	v_pk_mul_f32 v[30:31], v[30:31], v[34:35]
	v_lshlrev_b32_e32 v34, 16, v36
	v_and_b32_e32 v35, 0xffff0000, v36
	v_pk_mul_f32 v[28:29], v[28:29], v[40:41]
	v_pk_mul_f32 v[34:35], v[24:25], v[34:35]
	v_lshlrev_b32_e32 v24, 16, v37
	v_and_b32_e32 v25, 0xffff0000, v37
	v_pk_mul_f32 v[36:37], v[26:27], v[24:25]
	v_cvt_pk_bf16_f32 v24, v28, v29
	v_lshlrev_b64 v[28:29], 12, v[38:39]
	v_lshl_add_u64 v[28:29], s[12:13], 0, v[28:29]
	v_cvt_pk_bf16_f32 v25, v30, v31
	v_cvt_pk_bf16_f32 v26, v34, v35
	v_cvt_pk_bf16_f32 v27, v36, v37
	v_lshl_add_u64 v[28:29], v[28:29], 0, v[138:139]
	global_store_dwordx4 v[28:29], v[24:27], off
	s_waitcnt vmcnt(13)
	s_nop 1
	v_mov_b64_e32 v[24:25], v[178:179]
	v_mov_b64_e32 v[26:27], v[180:181]
	v_lshlrev_b32_e32 v30, 16, v24
	v_and_b32_e32 v31, 0xffff0000, v24
	v_lshlrev_b32_e32 v24, 16, v25
	v_and_b32_e32 v25, 0xffff0000, v25
	v_pk_mul_f32 v[22:23], v[22:23], v[24:25]
	v_lshlrev_b32_e32 v24, 16, v26
	v_and_b32_e32 v25, 0xffff0000, v26
	v_pk_mul_f32 v[24:25], v[16:17], v[24:25]
	v_lshlrev_b32_e32 v16, 16, v27
	v_and_b32_e32 v17, 0xffff0000, v27
	v_pk_mul_f32 v[20:21], v[20:21], v[30:31]
	v_pk_mul_f32 v[26:27], v[18:19], v[16:17]
	v_cvt_pk_bf16_f32 v16, v20, v21
	v_cvt_pk_bf16_f32 v17, v22, v23
	v_cvt_pk_bf16_f32 v18, v24, v25
	v_cvt_pk_bf16_f32 v19, v26, v27
	v_add_u32_e32 v22, 0xb0, v140
	global_store_dwordx4 v[28:29], v[16:19], off offset:256
	v_ashrrev_i32_e32 v23, 31, v22
	s_nop 0
	v_mad_i64_i32 v[16:17], s[2:3], v22, s26, v[142:143]
	v_lshl_add_u64 v[16:17], v[16:17], 0, v[138:139]
	s_waitcnt vmcnt(12)
	s_nop 1
	v_mov_b64_e32 v[18:19], v[182:183]
	v_mov_b64_e32 v[20:21], v[184:185]
	v_lshlrev_b32_e32 v24, 16, v18
	v_and_b32_e32 v25, 0xffff0000, v18
	v_lshlrev_b32_e32 v18, 16, v19
	v_and_b32_e32 v19, 0xffff0000, v19
	v_pk_mul_f32 v[14:15], v[14:15], v[18:19]
	v_lshlrev_b32_e32 v18, 16, v20
	v_and_b32_e32 v19, 0xffff0000, v20
	v_pk_mul_f32 v[12:13], v[12:13], v[24:25]
	v_pk_mul_f32 v[18:19], v[8:9], v[18:19]
	v_lshlrev_b32_e32 v8, 16, v21
	v_and_b32_e32 v9, 0xffff0000, v21
	v_pk_mul_f32 v[20:21], v[10:11], v[8:9]
	v_cvt_pk_bf16_f32 v8, v12, v13
	v_lshlrev_b64 v[12:13], 12, v[22:23]
	v_lshl_add_u64 v[12:13], s[12:13], 0, v[12:13]
	v_cvt_pk_bf16_f32 v9, v14, v15
	v_cvt_pk_bf16_f32 v10, v18, v19
	v_cvt_pk_bf16_f32 v11, v20, v21
	v_lshl_add_u64 v[12:13], v[12:13], 0, v[138:139]
	global_store_dwordx4 v[12:13], v[8:11], off
	s_waitcnt vmcnt(11)
	s_nop 1
	v_mov_b64_e32 v[8:9], v[186:187]
	v_mov_b64_e32 v[10:11], v[188:189]
	v_lshlrev_b32_e32 v14, 16, v8
	v_and_b32_e32 v15, 0xffff0000, v8
	v_lshlrev_b32_e32 v8, 16, v9
	v_and_b32_e32 v9, 0xffff0000, v9
	v_pk_mul_f32 v[6:7], v[6:7], v[8:9]
	v_lshlrev_b32_e32 v8, 16, v10
	v_and_b32_e32 v9, 0xffff0000, v10
	v_pk_mul_f32 v[8:9], v[0:1], v[8:9]
	v_lshlrev_b32_e32 v0, 16, v11
	v_and_b32_e32 v1, 0xffff0000, v11
	v_pk_mul_f32 v[4:5], v[4:5], v[14:15]
	v_pk_mul_f32 v[10:11], v[2:3], v[0:1]
	v_cvt_pk_bf16_f32 v0, v4, v5
	v_cvt_pk_bf16_f32 v1, v6, v7
	v_cvt_pk_bf16_f32 v2, v8, v9
	v_cvt_pk_bf16_f32 v3, v10, v11
	global_store_dwordx4 v[12:13], v[0:3], off offset:256
	s_cbranch_vccnz .LBB0_229
	s_andn2_b64 vcc, exec, s[6:7]
	s_cbranch_vccnz .LBB0_228
	s_barrier
	s_branch .LBB0_228
